# on top of the peeled first K-iteration: the trailing half-workgroup takes its inter-unit extra barrier after the next unit's header computation instead of before it
# baseline (speedup 1.0000x reference)
.LBB0_196:
	s_mov_b64 s[40:41], 0x80
	s_and_b32 s1, s3, 3
	s_add_i32 m0, s15, 0x18000
	v_lshl_add_u64 v[6:7], v[6:7], 0, s[40:41]
	s_lshl_b32 s56, s4, 6
	s_lshl_b32 s3, s4, 13
	s_lshl_b32 s6, s1, 12
	s_waitcnt vmcnt(2)
	s_barrier
	global_load_lds_dwordx4 v[6:7], off
	v_lshl_add_u64 v[4:5], v[4:5], 0, s[40:41]
	s_add_i32 m0, s15, 0x1a000
	s_add_i32 s57, s15, 0x8000
	s_add_i32 s58, s15, 0xa000
	global_load_lds_dwordx4 v[4:5], off
	v_lshl_add_u64 v[0:1], v[0:1], 0, s[40:41]
	s_mov_b32 m0, s57
	s_add_u32 s4, s80, 0x40080
	global_load_lds_dwordx4 v[0:1], off
	v_lshl_add_u64 v[0:1], v[2:3], 0, s[40:41]
	s_mov_b32 m0, s58
	s_addc_u32 s5, s81, 0
	global_load_lds_dwordx4 v[0:1], off
	s_add_i32 m0, s15, 0x1c000
	v_lshl_add_u64 v[0:1], s[4:5], 0, v[178:179]
	global_load_lds_dwordx4 v[0:1], off
	v_lshl_add_u64 v[0:1], s[4:5], 0, v[182:183]
	s_add_i32 m0, s15, 0x1e000
	v_and_b32_e32 v187, 15, v8
	global_load_lds_dwordx4 v[0:1], off
	v_bfe_u32 v1, v8, 4, 2
	v_lshlrev_b32_e32 v2, 4, v1
	v_lshlrev_b32_e32 v3, 2, v8
	v_lshlrev_b32_e32 v0, 3, v1
	v_lshl_or_b32 v2, v187, 6, v2
	v_and_b32_e32 v3, 32, v3
	v_bitop3_b32 v212, v2, s6, v3 bitop3:0xde
	v_cmp_gt_u32_e64 s[6:7], 2, v1
	v_cmp_eq_u32_e32 vcc, 0, v1
	v_lshl_or_b32 v1, s1, 5, v0
	v_or_b32_e32 v217, 0xfffffd00, v1
	v_lshlrev_b32_e32 v1, 14, v9
	v_and_b32_e32 v1, 0xffff8000, v1
	v_bitop3_b32 v4, v2, s3, v3 bitop3:0xde
	v_lshl_add_u32 v1, v10, 11, v1
	v_and_b32_e32 v2, 1, v9
	v_lshl_or_b32 v1, v2, 6, v1
	v_lshl_add_u32 v192, v11, 1, v1
	v_lshlrev_b32_e32 v1, 14, v12
	v_and_b32_e32 v1, 0xffff8000, v1
	s_waitcnt vmcnt(6)
	s_cmpk_lt_u32 s2, 0x100
	v_lshl_add_u32 v1, v13, 11, v1
	v_and_b32_e32 v2, 1, v12
	s_cselect_b64 s[42:43], -1, 0
	v_lshl_or_b32 v213, s1, 6, v0
	v_and_b32_e32 v216, 1, v8
	v_cndmask_b32_e64 v188, 1.0, -1.0, vcc
	v_lshl_or_b32 v1, v2, 6, v1
	s_add_i32 s59, 0, 0x10000
	s_add_i32 s65, 0, 0x14000
	v_lshlrev_b32_e32 v221, 2, v0
	v_mbcnt_lo_u32_b32 v0, -1, 0
	v_or_b32_e32 v214, 0xfffffc00, v213
	v_cmp_eq_u32_e64 s[4:5], 0, v216
	v_lshlrev_b32_e32 v186, 5, v216
	v_mov_b32_e32 v189, v188
	v_mov_b32_e32 v190, v188
	v_mov_b32_e32 v191, v188
	v_mov_b32_e32 v193, v185
	v_lshl_add_u32 v194, v14, 1, v1
	v_mov_b32_e32 v195, v185
	v_mov_b64_e32 v[196:197], 0x500
	v_mov_b64_e32 v[198:199], 0x4ff
	v_add_u32_e32 v218, s59, v212
	v_add_u32_e32 v219, s65, v212
	v_add_u32_e32 v220, 0, v4
	v_mov_b32_e32 v222, 0x358637bd
	s_mov_b64 s[70:71], 0x1000
	s_movk_i32 s84, 0x1000
	v_mbcnt_hi_u32_b32 v223, -1, v0
	v_mov_b32_e32 v224, 0x3e38aa3b
	v_mov_b32_e32 v225, 0x800
	s_barrier
	s_mov_b32 s98, 0
	s_branch .LBB0_199

.LBB0_201:
	s_ashr_i32 s75, s74, 31
	s_lshl_b64 s[2:3], s[74:75], 19
	s_add_u32 s76, s60, s2
	s_addc_u32 s77, s61, s3
	s_and_b64 s[2:3], s[8:9], exec
	s_cselect_b32 s1, s77, s13
	s_cselect_b32 s2, s76, s12
	s_ashr_i32 s73, s72, 31
	s_lshl_b64 s[34:35], s[72:73], 19
	s_add_u32 s78, s36, s34
	s_addc_u32 s79, s37, s35
	s_and_b64 s[34:35], s[8:9], exec
	s_cselect_b32 s3, s79, s81
	s_cselect_b32 s34, s78, s80
	s_add_u32 s12, s12, 0x40080
	s_addc_u32 s13, s13, 0
	s_add_u32 s35, s80, 0x100
	s_addc_u32 s66, s81, 0
	s_mov_b32 s68, -2
	s_cmp_eq_u32 s98, 0
	s_cbranch_scc1 .Ltb_skip_0
	s_barrier
	s_mov_b32 s98, 0
.Ltb_skip_0:
	ds_read_b128 v[112:115], v218
	ds_read_b128 v[116:119], v218 offset:1024
	ds_read_b128 v[120:123], v218 offset:2048
	ds_read_b128 v[124:127], v218 offset:3072
	s_waitcnt vmcnt(0)
	ds_read_b128 v[128:131], v219
	ds_read_b128 v[132:135], v219 offset:1024
	ds_read_b128 v[136:139], v219 offset:2048
	ds_read_b128 v[140:143], v219 offset:3072
	s_add_u32 s69, s12, 0xfffc0080
	s_addc_u32 s73, s13, -1
	s_cmp_eq_u32 s68, 12
	s_cselect_b32 s83, s1, s73
	s_cselect_b32 s82, s2, s69
	s_cselect_b32 s81, s3, s66
	s_cselect_b32 s80, s34, s35
	v_lshl_add_u64 v[230:231], s[12:13], 0, v[192:193]
	s_add_i32 m0, s15, 0xc000
	ds_read_b128 v[152:155], v220
	ds_read_b128 v[156:159], v220 offset:1024
	ds_read_b128 v[160:163], v220 offset:2048
	ds_read_b128 v[164:167], v220 offset:3072
	ds_read_b128 v[200:203], v220 offset:4096
	ds_read_b128 v[204:207], v220 offset:5120
	ds_read_b128 v[208:211], v220 offset:6144
	ds_read_b128 v[226:229], v220 offset:7168
	global_load_lds_dwordx4 v[230:231], off
	v_lshl_add_u64 v[230:231], s[12:13], 0, v[194:195]
	s_add_i32 m0, s15, 0xe000
	s_nop 0
	global_load_lds_dwordx4 v[230:231], off
	s_waitcnt vmcnt(8)
	s_waitcnt lgkmcnt(0)
	s_barrier
	s_setprio 1
	s_waitcnt lgkmcnt(0)
	v_mfma_f32_16x16x32_bf16 v[172:175], v[112:115], v[152:155], 0
	v_mfma_f32_16x16x32_bf16 v[172:175], v[116:119], v[156:159], v[172:175]
	v_mfma_f32_16x16x32_bf16 v[168:171], v[120:123], v[152:155], 0
	v_mfma_f32_16x16x32_bf16 v[168:171], v[124:127], v[156:159], v[168:171]
	v_mfma_f32_16x16x32_bf16 v[104:107], v[120:123], v[160:163], 0
	v_mfma_f32_16x16x32_bf16 v[104:107], v[124:127], v[164:167], v[104:107]
	v_mfma_f32_16x16x32_bf16 v[108:111], v[112:115], v[160:163], 0
	v_mfma_f32_16x16x32_bf16 v[108:111], v[116:119], v[164:167], v[108:111]
	v_mfma_f32_16x16x32_bf16 v[92:95], v[112:115], v[200:203], 0
	v_mfma_f32_16x16x32_bf16 v[92:95], v[116:119], v[204:207], v[92:95]
	v_mfma_f32_16x16x32_bf16 v[88:91], v[120:123], v[200:203], 0
	v_mfma_f32_16x16x32_bf16 v[88:91], v[124:127], v[204:207], v[88:91]
	v_mfma_f32_16x16x32_bf16 v[72:75], v[120:123], v[208:211], 0
	v_mfma_f32_16x16x32_bf16 v[72:75], v[124:127], v[226:229], v[72:75]
	v_mfma_f32_16x16x32_bf16 v[76:79], v[112:115], v[208:211], 0
	v_mfma_f32_16x16x32_bf16 v[76:79], v[116:119], v[226:229], v[76:79]
	s_setprio 0
	s_setprio 1
	v_mfma_f32_16x16x32_bf16 v[148:151], v[128:131], v[152:155], 0
	v_mfma_f32_16x16x32_bf16 v[148:151], v[132:135], v[156:159], v[148:151]
	v_mfma_f32_16x16x32_bf16 v[144:147], v[136:139], v[152:155], 0
	v_mfma_f32_16x16x32_bf16 v[144:147], v[140:143], v[156:159], v[144:147]
	v_mfma_f32_16x16x32_bf16 v[96:99], v[136:139], v[160:163], 0
	v_mfma_f32_16x16x32_bf16 v[96:99], v[140:143], v[164:167], v[96:99]
	v_mfma_f32_16x16x32_bf16 v[100:103], v[128:131], v[160:163], 0
	v_mfma_f32_16x16x32_bf16 v[100:103], v[132:135], v[164:167], v[100:103]
	v_mfma_f32_16x16x32_bf16 v[84:87], v[128:131], v[200:203], 0
	v_mfma_f32_16x16x32_bf16 v[84:87], v[132:135], v[204:207], v[84:87]
	v_mfma_f32_16x16x32_bf16 v[80:83], v[136:139], v[200:203], 0
	v_mfma_f32_16x16x32_bf16 v[80:83], v[140:143], v[204:207], v[80:83]
	v_mfma_f32_16x16x32_bf16 v[64:67], v[136:139], v[208:211], 0
	v_mfma_f32_16x16x32_bf16 v[64:67], v[140:143], v[226:229], v[64:67]
	v_mfma_f32_16x16x32_bf16 v[68:71], v[128:131], v[208:211], 0
	v_mfma_f32_16x16x32_bf16 v[68:71], v[132:135], v[226:229], v[68:71]
	s_setprio 0
	s_barrier
	s_add_i32 s69, s59, s14
	v_lshl_add_u64 v[230:231], s[80:81], 0, v[178:179]
	s_mov_b32 m0, s69
	ds_read_b128 v[152:155], v220 offset:16384
	ds_read_b128 v[156:159], v220 offset:17408
	ds_read_b128 v[160:163], v220 offset:18432
	ds_read_b128 v[164:167], v220 offset:19456
	ds_read_b128 v[200:203], v220 offset:20480
	ds_read_b128 v[204:207], v220 offset:21504
	ds_read_b128 v[208:211], v220 offset:22528
	ds_read_b128 v[226:229], v220 offset:23552
	global_load_lds_dwordx4 v[230:231], off
	s_add_i32 m0, s69, 0x2000
	s_add_u32 s86, s80, 0x40000
	v_lshl_add_u64 v[232:233], s[80:81], 0, v[182:183]
	s_addc_u32 s87, s81, 0
	s_add_i32 s69, s65, s14
	global_load_lds_dwordx4 v[232:233], off
	v_lshl_add_u64 v[234:235], s[86:87], 0, v[178:179]
	s_mov_b32 m0, s69
	v_lshl_add_u64 v[236:237], s[82:83], 0, v[180:181]
	global_load_lds_dwordx4 v[234:235], off
	v_lshl_add_u64 v[234:235], s[86:87], 0, v[182:183]
	s_add_i32 m0, s69, 0x2000
	s_nop 0
	global_load_lds_dwordx4 v[234:235], off
	v_lshl_add_u64 v[234:235], s[82:83], 0, v[176:177]
	s_mov_b32 m0, s15
	s_nop 0
	global_load_lds_dwordx4 v[234:235], off
	s_mov_b32 m0, s52
	s_nop 0
	global_load_lds_dwordx4 v[236:237], off
	s_waitcnt vmcnt(8)
	s_waitcnt lgkmcnt(0)
	s_barrier
	s_setprio 1
	s_waitcnt lgkmcnt(0)
	v_mfma_f32_16x16x32_bf16 v[60:63], v[112:115], v[152:155], 0
	v_mfma_f32_16x16x32_bf16 v[60:63], v[116:119], v[156:159], v[60:63]
	v_mfma_f32_16x16x32_bf16 v[56:59], v[120:123], v[152:155], 0
	v_mfma_f32_16x16x32_bf16 v[56:59], v[124:127], v[156:159], v[56:59]
	v_mfma_f32_16x16x32_bf16 v[40:43], v[120:123], v[160:163], 0
	v_mfma_f32_16x16x32_bf16 v[40:43], v[124:127], v[164:167], v[40:43]
	v_mfma_f32_16x16x32_bf16 v[44:47], v[112:115], v[160:163], 0
	v_mfma_f32_16x16x32_bf16 v[44:47], v[116:119], v[164:167], v[44:47]
	v_mfma_f32_16x16x32_bf16 v[28:31], v[112:115], v[200:203], 0
	v_mfma_f32_16x16x32_bf16 v[28:31], v[116:119], v[204:207], v[28:31]
	v_mfma_f32_16x16x32_bf16 v[24:27], v[120:123], v[200:203], 0
	v_mfma_f32_16x16x32_bf16 v[24:27], v[124:127], v[204:207], v[24:27]
	v_mfma_f32_16x16x32_bf16 v[8:11], v[120:123], v[208:211], 0
	v_mfma_f32_16x16x32_bf16 v[8:11], v[124:127], v[226:229], v[8:11]
	v_mfma_f32_16x16x32_bf16 v[12:15], v[112:115], v[208:211], 0
	v_mfma_f32_16x16x32_bf16 v[12:15], v[116:119], v[226:229], v[12:15]
	s_setprio 0
	s_setprio 1
	v_mfma_f32_16x16x32_bf16 v[52:55], v[128:131], v[152:155], 0
	v_mfma_f32_16x16x32_bf16 v[52:55], v[132:135], v[156:159], v[52:55]
	v_mfma_f32_16x16x32_bf16 v[48:51], v[136:139], v[152:155], 0
	v_mfma_f32_16x16x32_bf16 v[48:51], v[140:143], v[156:159], v[48:51]
	v_mfma_f32_16x16x32_bf16 v[32:35], v[136:139], v[160:163], 0
	v_mfma_f32_16x16x32_bf16 v[32:35], v[140:143], v[164:167], v[32:35]
	v_mfma_f32_16x16x32_bf16 v[36:39], v[128:131], v[160:163], 0
	v_mfma_f32_16x16x32_bf16 v[36:39], v[132:135], v[164:167], v[36:39]
	v_mfma_f32_16x16x32_bf16 v[20:23], v[128:131], v[200:203], 0
	v_mfma_f32_16x16x32_bf16 v[20:23], v[132:135], v[204:207], v[20:23]
	v_mfma_f32_16x16x32_bf16 v[16:19], v[136:139], v[200:203], 0
	v_mfma_f32_16x16x32_bf16 v[16:19], v[140:143], v[204:207], v[16:19]
	v_mfma_f32_16x16x32_bf16 v[0:3], v[136:139], v[208:211], 0
	v_mfma_f32_16x16x32_bf16 v[0:3], v[140:143], v[226:229], v[0:3]
	v_mfma_f32_16x16x32_bf16 v[4:7], v[128:131], v[208:211], 0
	v_mfma_f32_16x16x32_bf16 v[4:7], v[132:135], v[226:229], v[4:7]
	s_setprio 0
	s_barrier
	s_add_i32 s69, 0, 0x18000
	s_add_i32 s73, 0, 0x1c000
	v_add_u32_e32 v124, s69, v212
	v_add_u32_e32 v140, s73, v212
	ds_read_b128 v[112:115], v124
	ds_read_b128 v[116:119], v124 offset:1024
	ds_read_b128 v[120:123], v124 offset:2048
	ds_read_b128 v[124:127], v124 offset:3072
	ds_read_b128 v[128:131], v140
	ds_read_b128 v[132:135], v140 offset:1024
	ds_read_b128 v[136:139], v140 offset:2048
	ds_read_b128 v[140:143], v140 offset:3072
	s_add_u32 s82, s82, 0x40000
	s_addc_u32 s83, s83, 0
	s_mov_b32 m0, s53
	v_lshl_add_u64 v[238:239], s[82:83], 0, v[176:177]
	ds_read_b128 v[152:155], v220 offset:32768
	ds_read_b128 v[156:159], v220 offset:33792
	ds_read_b128 v[160:163], v220 offset:34816
	ds_read_b128 v[164:167], v220 offset:35840
	ds_read_b128 v[200:203], v220 offset:36864
	ds_read_b128 v[204:207], v220 offset:37888
	ds_read_b128 v[208:211], v220 offset:38912
	ds_read_b128 v[226:229], v220 offset:39936
	global_load_lds_dwordx4 v[238:239], off
	v_lshl_add_u64 v[238:239], s[82:83], 0, v[180:181]
	s_mov_b32 m0, s54
	s_nop 0
	global_load_lds_dwordx4 v[238:239], off
	s_waitcnt vmcnt(8)
	s_waitcnt lgkmcnt(0)
	s_barrier
	s_setprio 1
	s_waitcnt lgkmcnt(0)
	v_mfma_f32_16x16x32_bf16 v[172:175], v[112:115], v[152:155], v[172:175]
	v_mfma_f32_16x16x32_bf16 v[172:175], v[116:119], v[156:159], v[172:175]
	v_mfma_f32_16x16x32_bf16 v[168:171], v[120:123], v[152:155], v[168:171]
	v_mfma_f32_16x16x32_bf16 v[168:171], v[124:127], v[156:159], v[168:171]
	v_mfma_f32_16x16x32_bf16 v[104:107], v[120:123], v[160:163], v[104:107]
	v_mfma_f32_16x16x32_bf16 v[104:107], v[124:127], v[164:167], v[104:107]
	v_mfma_f32_16x16x32_bf16 v[108:111], v[112:115], v[160:163], v[108:111]
	v_mfma_f32_16x16x32_bf16 v[108:111], v[116:119], v[164:167], v[108:111]
	v_mfma_f32_16x16x32_bf16 v[92:95], v[112:115], v[200:203], v[92:95]
	v_mfma_f32_16x16x32_bf16 v[92:95], v[116:119], v[204:207], v[92:95]
	v_mfma_f32_16x16x32_bf16 v[88:91], v[120:123], v[200:203], v[88:91]
	v_mfma_f32_16x16x32_bf16 v[88:91], v[124:127], v[204:207], v[88:91]
	v_mfma_f32_16x16x32_bf16 v[72:75], v[120:123], v[208:211], v[72:75]
	v_mfma_f32_16x16x32_bf16 v[72:75], v[124:127], v[226:229], v[72:75]
	v_mfma_f32_16x16x32_bf16 v[76:79], v[112:115], v[208:211], v[76:79]
	v_mfma_f32_16x16x32_bf16 v[76:79], v[116:119], v[226:229], v[76:79]
	s_setprio 0
	s_setprio 1
	v_mfma_f32_16x16x32_bf16 v[148:151], v[128:131], v[152:155], v[148:151]
	v_mfma_f32_16x16x32_bf16 v[148:151], v[132:135], v[156:159], v[148:151]
	v_mfma_f32_16x16x32_bf16 v[144:147], v[136:139], v[152:155], v[144:147]
	v_mfma_f32_16x16x32_bf16 v[144:147], v[140:143], v[156:159], v[144:147]
	v_mfma_f32_16x16x32_bf16 v[96:99], v[136:139], v[160:163], v[96:99]
	v_mfma_f32_16x16x32_bf16 v[96:99], v[140:143], v[164:167], v[96:99]
	v_mfma_f32_16x16x32_bf16 v[100:103], v[128:131], v[160:163], v[100:103]
	v_mfma_f32_16x16x32_bf16 v[100:103], v[132:135], v[164:167], v[100:103]
	v_mfma_f32_16x16x32_bf16 v[84:87], v[128:131], v[200:203], v[84:87]
	v_mfma_f32_16x16x32_bf16 v[84:87], v[132:135], v[204:207], v[84:87]
	v_mfma_f32_16x16x32_bf16 v[80:83], v[136:139], v[200:203], v[80:83]
	v_mfma_f32_16x16x32_bf16 v[80:83], v[140:143], v[204:207], v[80:83]
	v_mfma_f32_16x16x32_bf16 v[64:67], v[136:139], v[208:211], v[64:67]
	v_mfma_f32_16x16x32_bf16 v[64:67], v[140:143], v[226:229], v[64:67]
	v_mfma_f32_16x16x32_bf16 v[68:71], v[128:131], v[208:211], v[68:71]
	v_mfma_f32_16x16x32_bf16 v[68:71], v[132:135], v[226:229], v[68:71]
	s_setprio 0
	s_barrier
	s_add_i32 s69, s69, s14
	v_lshl_add_u64 v[230:231], v[230:231], 0, s[40:41]
	s_mov_b32 m0, s69
	ds_read_b128 v[152:155], v220 offset:49152
	ds_read_b128 v[156:159], v220 offset:50176
	ds_read_b128 v[160:163], v220 offset:51200
	ds_read_b128 v[164:167], v220 offset:52224
	ds_read_b128 v[200:203], v220 offset:53248
	ds_read_b128 v[204:207], v220 offset:54272
	ds_read_b128 v[208:211], v220 offset:55296
	ds_read_b128 v[226:229], v220 offset:56320
	global_load_lds_dwordx4 v[230:231], off
	s_add_i32 m0, s69, 0x2000
	s_add_u32 s80, s80, 0x40080
	v_lshl_add_u64 v[230:231], v[232:233], 0, s[40:41]
	s_addc_u32 s81, s81, 0
	s_add_i32 s69, s73, s14
	global_load_lds_dwordx4 v[230:231], off
	v_lshl_add_u64 v[230:231], s[80:81], 0, v[178:179]
	s_mov_b32 m0, s69
	s_nop 0
	global_load_lds_dwordx4 v[230:231], off
	v_lshl_add_u64 v[230:231], s[80:81], 0, v[182:183]
	s_add_i32 m0, s69, 0x2000
	s_nop 0
	global_load_lds_dwordx4 v[230:231], off
	v_lshl_add_u64 v[230:231], v[234:235], 0, s[40:41]
	s_mov_b32 m0, s57
	s_nop 0
	global_load_lds_dwordx4 v[230:231], off
	v_lshl_add_u64 v[230:231], v[236:237], 0, s[40:41]
	s_mov_b32 m0, s58
	s_nop 0
	global_load_lds_dwordx4 v[230:231], off
	s_waitcnt vmcnt(8)
	s_waitcnt lgkmcnt(0)
	s_barrier
	s_setprio 1
	s_waitcnt lgkmcnt(0)
	v_mfma_f32_16x16x32_bf16 v[60:63], v[112:115], v[152:155], v[60:63]
	v_mfma_f32_16x16x32_bf16 v[60:63], v[116:119], v[156:159], v[60:63]
	v_mfma_f32_16x16x32_bf16 v[56:59], v[120:123], v[152:155], v[56:59]
	v_mfma_f32_16x16x32_bf16 v[56:59], v[124:127], v[156:159], v[56:59]
	v_mfma_f32_16x16x32_bf16 v[40:43], v[120:123], v[160:163], v[40:43]
	v_mfma_f32_16x16x32_bf16 v[40:43], v[124:127], v[164:167], v[40:43]
	v_mfma_f32_16x16x32_bf16 v[44:47], v[112:115], v[160:163], v[44:47]
	v_mfma_f32_16x16x32_bf16 v[44:47], v[116:119], v[164:167], v[44:47]
	v_mfma_f32_16x16x32_bf16 v[28:31], v[112:115], v[200:203], v[28:31]
	v_mfma_f32_16x16x32_bf16 v[28:31], v[116:119], v[204:207], v[28:31]
	v_mfma_f32_16x16x32_bf16 v[24:27], v[120:123], v[200:203], v[24:27]
	v_mfma_f32_16x16x32_bf16 v[24:27], v[124:127], v[204:207], v[24:27]
	v_mfma_f32_16x16x32_bf16 v[8:11], v[120:123], v[208:211], v[8:11]
	v_mfma_f32_16x16x32_bf16 v[8:11], v[124:127], v[226:229], v[8:11]
	v_mfma_f32_16x16x32_bf16 v[12:15], v[112:115], v[208:211], v[12:15]
	v_mfma_f32_16x16x32_bf16 v[12:15], v[116:119], v[226:229], v[12:15]
	s_setprio 0
	s_setprio 1
	v_mfma_f32_16x16x32_bf16 v[52:55], v[128:131], v[152:155], v[52:55]
	v_mfma_f32_16x16x32_bf16 v[52:55], v[132:135], v[156:159], v[52:55]
	v_mfma_f32_16x16x32_bf16 v[48:51], v[136:139], v[152:155], v[48:51]
	v_mfma_f32_16x16x32_bf16 v[48:51], v[140:143], v[156:159], v[48:51]
	v_mfma_f32_16x16x32_bf16 v[32:35], v[136:139], v[160:163], v[32:35]
	v_mfma_f32_16x16x32_bf16 v[32:35], v[140:143], v[164:167], v[32:35]
	v_mfma_f32_16x16x32_bf16 v[36:39], v[128:131], v[160:163], v[36:39]
	v_mfma_f32_16x16x32_bf16 v[36:39], v[132:135], v[164:167], v[36:39]
	v_mfma_f32_16x16x32_bf16 v[20:23], v[128:131], v[200:203], v[20:23]
	v_mfma_f32_16x16x32_bf16 v[20:23], v[132:135], v[204:207], v[20:23]
	v_mfma_f32_16x16x32_bf16 v[16:19], v[136:139], v[200:203], v[16:19]
	v_mfma_f32_16x16x32_bf16 v[16:19], v[140:143], v[204:207], v[16:19]
	v_mfma_f32_16x16x32_bf16 v[0:3], v[136:139], v[208:211], v[0:3]
	v_mfma_f32_16x16x32_bf16 v[0:3], v[140:143], v[226:229], v[0:3]
	v_mfma_f32_16x16x32_bf16 v[4:7], v[128:131], v[208:211], v[4:7]
	v_mfma_f32_16x16x32_bf16 v[4:7], v[132:135], v[226:229], v[4:7]
	s_setprio 0
	s_barrier
	s_add_i32 s68, s68, 2
	s_add_u32 s12, s12, 0x100
	s_addc_u32 s13, s13, 0
	s_add_u32 s35, s35, 0x100
	s_addc_u32 s66, s66, 0

.LBB0_253:
	s_andn2_b64 vcc, exec, s[8:9]
	s_mov_b64 s[0:1], -1
	s_cbranch_vccnz .LBB0_198
	s_andn2_b64 vcc, exec, s[38:39]
	s_cbranch_vccnz .LBB0_197
	s_mov_b32 s98, 1
	s_branch .LBB0_197

.LBB0_636:
	s_mov_b64 s[24:25], 0x80
	s_and_b32 s48, s0, 3
	s_add_i32 m0, s3, 0x18000
	v_lshl_add_u64 v[6:7], v[6:7], 0, s[24:25]
	s_lshl_b32 s0, s1, 13
	s_lshl_b32 s7, s48, 12
	s_waitcnt vmcnt(2)
	s_barrier
	global_load_lds_dwordx4 v[6:7], off
	v_lshl_add_u64 v[4:5], v[4:5], 0, s[24:25]
	s_add_i32 m0, s3, 0x1a000
	s_add_i32 s49, s3, 0x8000
	s_add_i32 s50, s3, 0xa000
	global_load_lds_dwordx4 v[4:5], off
	v_lshl_add_u64 v[0:1], v[0:1], 0, s[24:25]
	s_mov_b32 m0, s49
	s_add_u32 s8, s44, 0x40080
	global_load_lds_dwordx4 v[0:1], off
	v_lshl_add_u64 v[0:1], v[2:3], 0, s[24:25]
	s_mov_b32 m0, s50
	s_addc_u32 s9, s45, 0
	global_load_lds_dwordx4 v[0:1], off
	s_add_i32 m0, s3, 0x1c000
	v_lshl_add_u64 v[0:1], s[8:9], 0, v[186:187]
	global_load_lds_dwordx4 v[0:1], off
	v_lshl_add_u64 v[0:1], s[8:9], 0, v[190:191]
	s_add_i32 m0, s3, 0x1e000
	s_cmpk_lt_u32 s6, 0x100
	global_load_lds_dwordx4 v[0:1], off
	v_bfe_u32 v1, v8, 4, 2
	v_and_b32_e32 v0, 15, v8
	v_lshlrev_b32_e32 v3, 4, v1
	v_lshl_or_b32 v207, s1, 6, v0
	v_lshl_or_b32 v0, v0, 6, v3
	v_lshlrev_b32_e32 v3, 2, v8
	v_and_b32_e32 v3, 32, v3
	v_lshlrev_b32_e32 v2, 3, v1
	v_bitop3_b32 v4, v0, s0, v3 bitop3:0xde
	v_cmp_eq_u32_e64 s[0:1], 0, v1
	v_lshlrev_b32_e32 v1, 14, v9
	v_and_b32_e32 v1, 0xffff8000, v1
	v_lshl_or_b32 v227, s48, 6, v2
	v_lshl_add_u32 v1, v10, 11, v1
	v_and_b32_e32 v2, 1, v9
	v_lshl_or_b32 v1, v2, 6, v1
	v_lshl_add_u32 v194, v11, 1, v1
	v_lshlrev_b32_e32 v1, 14, v12
	v_and_b32_e32 v1, 0xffff8000, v1
	s_waitcnt vmcnt(6)
	v_and_b32_e32 v233, 1, v8
	v_lshl_add_u32 v1, v13, 11, v1
	v_and_b32_e32 v2, 1, v12
	v_bitop3_b32 v211, v0, s7, v3 bitop3:0xde
	s_cselect_b64 s[26:27], -1, 0
	v_lshlrev_b32_e32 v0, 5, v233
	v_lshl_or_b32 v1, v2, 6, v1
	s_add_i32 s51, 0, 0x10000
	s_add_i32 s52, 0, 0x14000
	v_cmp_eq_u32_e64 s[6:7], 0, v233
	v_mov_b32_e32 v195, v193
	v_lshl_add_u32 v196, v14, 1, v1
	v_mov_b32_e32 v197, v193
	v_mov_b64_e32 v[198:199], 0x200
	v_mov_b64_e32 v[200:201], 0x1ff
	v_add_u32_e32 v236, s51, v211
	v_add_u32_e32 v237, s52, v211
	v_add_u32_e32 v238, 0, v4
	v_lshlrev_b32_e32 v192, 1, v0
	s_mov_b32 s53, 0
	s_barrier
	s_mov_b32 s98, 0
	s_branch .LBB0_639

.LBB0_645:
	s_ashr_i32 s31, s30, 31
	s_lshl_b64 s[36:37], s[30:31], 19
	s_add_u32 s36, s92, s36
	s_addc_u32 s37, s93, s37
	s_and_b64 s[38:39], s[8:9], exec
	s_cselect_b32 s31, s37, s43
	s_cselect_b32 s41, s36, s42
	s_ashr_i32 s29, s28, 31
	s_lshl_b64 s[38:39], s[28:29], 19
	s_add_u32 s38, s10, s38
	s_addc_u32 s39, s11, s39
	s_and_b64 s[46:47], s[8:9], exec
	s_cselect_b32 s29, s39, s45
	s_cselect_b32 s54, s38, s44
	s_add_u32 s42, s42, 0x40080
	s_addc_u32 s43, s43, 0
	s_add_u32 s55, s44, 0x100
	s_addc_u32 s56, s45, 0
	s_mov_b32 s57, -2
	s_waitcnt lgkmcnt(0)
	s_cmp_eq_u32 s98, 0
	s_cbranch_scc1 .Ltb_skip_1
	s_barrier
	s_mov_b32 s98, 0
.Ltb_skip_1:
	ds_read_b128 v[88:91], v236
	ds_read_b128 v[100:103], v236 offset:1024
	ds_read_b128 v[112:115], v236 offset:2048
	ds_read_b128 v[124:127], v236 offset:3072
	ds_read_b128 v[136:139], v237
	ds_read_b128 v[148:151], v237 offset:1024
	ds_read_b128 v[152:155], v237 offset:2048
	ds_read_b128 v[156:159], v237 offset:3072
	s_add_u32 s44, s42, 0xfffc0080
	s_addc_u32 s45, s43, -1
	s_cmp_eq_u32 s57, 12
	s_cselect_b32 s47, s31, s45
	s_cselect_b32 s46, s41, s44
	s_cselect_b32 s45, s29, s56
	s_cselect_b32 s44, s54, s55
	v_lshl_add_u64 v[208:209], s[42:43], 0, v[194:195]
	s_add_i32 m0, s3, 0xc000
	ds_read_b128 v[160:163], v238
	ds_read_b128 v[164:167], v238 offset:1024
	ds_read_b128 v[168:171], v238 offset:2048
	ds_read_b128 v[172:175], v238 offset:3072
	ds_read_b128 v[176:179], v238 offset:4096
	ds_read_b128 v[180:183], v238 offset:5120
	ds_read_b128 v[202:205], v238 offset:6144
	ds_read_b128 v[228:231], v238 offset:7168
	global_load_lds_dwordx4 v[208:209], off
	v_lshl_add_u64 v[208:209], s[42:43], 0, v[196:197]
	s_add_i32 m0, s3, 0xe000
	s_nop 0
	global_load_lds_dwordx4 v[208:209], off
	s_waitcnt vmcnt(8)
	s_waitcnt lgkmcnt(0)
	s_barrier
	s_setprio 1
	s_waitcnt lgkmcnt(0)
	v_mfma_f32_16x16x32_bf16 v[144:147], v[88:91], v[160:163], 0
	v_mfma_f32_16x16x32_bf16 v[144:147], v[100:103], v[164:167], v[144:147]
	v_mfma_f32_16x16x32_bf16 v[140:143], v[112:115], v[160:163], 0
	v_mfma_f32_16x16x32_bf16 v[140:143], v[124:127], v[164:167], v[140:143]
	v_mfma_f32_16x16x32_bf16 v[116:119], v[112:115], v[168:171], 0
	v_mfma_f32_16x16x32_bf16 v[116:119], v[124:127], v[172:175], v[116:119]
	v_mfma_f32_16x16x32_bf16 v[120:123], v[88:91], v[168:171], 0
	v_mfma_f32_16x16x32_bf16 v[120:123], v[100:103], v[172:175], v[120:123]
	v_mfma_f32_16x16x32_bf16 v[96:99], v[88:91], v[176:179], 0
	v_mfma_f32_16x16x32_bf16 v[96:99], v[100:103], v[180:183], v[96:99]
	v_mfma_f32_16x16x32_bf16 v[92:95], v[112:115], v[176:179], 0
	v_mfma_f32_16x16x32_bf16 v[92:95], v[124:127], v[180:183], v[92:95]
	v_mfma_f32_16x16x32_bf16 v[72:75], v[112:115], v[202:205], 0
	v_mfma_f32_16x16x32_bf16 v[72:75], v[124:127], v[228:231], v[72:75]
	v_mfma_f32_16x16x32_bf16 v[76:79], v[88:91], v[202:205], 0
	v_mfma_f32_16x16x32_bf16 v[76:79], v[100:103], v[228:231], v[76:79]
	s_setprio 0
	s_setprio 1
	v_mfma_f32_16x16x32_bf16 v[132:135], v[136:139], v[160:163], 0
	v_mfma_f32_16x16x32_bf16 v[132:135], v[148:151], v[164:167], v[132:135]
	v_mfma_f32_16x16x32_bf16 v[128:131], v[152:155], v[160:163], 0
	v_mfma_f32_16x16x32_bf16 v[128:131], v[156:159], v[164:167], v[128:131]
	v_mfma_f32_16x16x32_bf16 v[104:107], v[152:155], v[168:171], 0
	v_mfma_f32_16x16x32_bf16 v[104:107], v[156:159], v[172:175], v[104:107]
	v_mfma_f32_16x16x32_bf16 v[108:111], v[136:139], v[168:171], 0
	v_mfma_f32_16x16x32_bf16 v[108:111], v[148:151], v[172:175], v[108:111]
	v_mfma_f32_16x16x32_bf16 v[84:87], v[136:139], v[176:179], 0
	v_mfma_f32_16x16x32_bf16 v[84:87], v[148:151], v[180:183], v[84:87]
	v_mfma_f32_16x16x32_bf16 v[80:83], v[152:155], v[176:179], 0
	v_mfma_f32_16x16x32_bf16 v[80:83], v[156:159], v[180:183], v[80:83]
	v_mfma_f32_16x16x32_bf16 v[64:67], v[152:155], v[202:205], 0
	v_mfma_f32_16x16x32_bf16 v[64:67], v[156:159], v[228:231], v[64:67]
	v_mfma_f32_16x16x32_bf16 v[68:71], v[136:139], v[202:205], 0
	v_mfma_f32_16x16x32_bf16 v[68:71], v[148:151], v[228:231], v[68:71]
	s_setprio 0
	s_barrier
	s_add_i32 s58, s51, s2
	v_lshl_add_u64 v[208:209], s[44:45], 0, v[186:187]
	s_mov_b32 m0, s58
	ds_read_b128 v[160:163], v238 offset:16384
	ds_read_b128 v[164:167], v238 offset:17408
	ds_read_b128 v[168:171], v238 offset:18432
	ds_read_b128 v[172:175], v238 offset:19456
	ds_read_b128 v[176:179], v238 offset:20480
	ds_read_b128 v[180:183], v238 offset:21504
	ds_read_b128 v[202:205], v238 offset:22528
	ds_read_b128 v[228:231], v238 offset:23552
	global_load_lds_dwordx4 v[208:209], off
	s_add_i32 m0, s58, 0x2000
	s_add_u32 s58, s44, 0x40000
	v_lshl_add_u64 v[212:213], s[44:45], 0, v[190:191]
	s_addc_u32 s59, s45, 0
	s_add_i32 s64, s52, s2
	global_load_lds_dwordx4 v[212:213], off
	v_lshl_add_u64 v[216:217], s[58:59], 0, v[186:187]
	s_mov_b32 m0, s64
	v_lshl_add_u64 v[220:221], s[46:47], 0, v[188:189]
	global_load_lds_dwordx4 v[216:217], off
	v_lshl_add_u64 v[216:217], s[58:59], 0, v[190:191]
	s_add_i32 m0, s64, 0x2000
	s_nop 0
	global_load_lds_dwordx4 v[216:217], off
	v_lshl_add_u64 v[216:217], s[46:47], 0, v[184:185]
	s_mov_b32 m0, s3
	s_nop 0
	global_load_lds_dwordx4 v[216:217], off
	s_mov_b32 m0, s33
	s_nop 0
	global_load_lds_dwordx4 v[220:221], off
	s_waitcnt vmcnt(8)
	s_waitcnt lgkmcnt(0)
	s_barrier
	s_setprio 1
	s_waitcnt lgkmcnt(0)
	v_mfma_f32_16x16x32_bf16 v[60:63], v[88:91], v[160:163], 0
	v_mfma_f32_16x16x32_bf16 v[60:63], v[100:103], v[164:167], v[60:63]
	v_mfma_f32_16x16x32_bf16 v[56:59], v[112:115], v[160:163], 0
	v_mfma_f32_16x16x32_bf16 v[56:59], v[124:127], v[164:167], v[56:59]
	v_mfma_f32_16x16x32_bf16 v[40:43], v[112:115], v[168:171], 0
	v_mfma_f32_16x16x32_bf16 v[40:43], v[124:127], v[172:175], v[40:43]
	v_mfma_f32_16x16x32_bf16 v[44:47], v[88:91], v[168:171], 0
	v_mfma_f32_16x16x32_bf16 v[44:47], v[100:103], v[172:175], v[44:47]
	v_mfma_f32_16x16x32_bf16 v[28:31], v[88:91], v[176:179], 0
	v_mfma_f32_16x16x32_bf16 v[28:31], v[100:103], v[180:183], v[28:31]
	v_mfma_f32_16x16x32_bf16 v[24:27], v[112:115], v[176:179], 0
	v_mfma_f32_16x16x32_bf16 v[24:27], v[124:127], v[180:183], v[24:27]
	v_mfma_f32_16x16x32_bf16 v[8:11], v[112:115], v[202:205], 0
	v_mfma_f32_16x16x32_bf16 v[8:11], v[124:127], v[228:231], v[8:11]
	v_mfma_f32_16x16x32_bf16 v[12:15], v[88:91], v[202:205], 0
	v_mfma_f32_16x16x32_bf16 v[12:15], v[100:103], v[228:231], v[12:15]
	s_setprio 0
	s_setprio 1
	v_mfma_f32_16x16x32_bf16 v[52:55], v[136:139], v[160:163], 0
	v_mfma_f32_16x16x32_bf16 v[52:55], v[148:151], v[164:167], v[52:55]
	v_mfma_f32_16x16x32_bf16 v[48:51], v[152:155], v[160:163], 0
	v_mfma_f32_16x16x32_bf16 v[48:51], v[156:159], v[164:167], v[48:51]
	v_mfma_f32_16x16x32_bf16 v[32:35], v[152:155], v[168:171], 0
	v_mfma_f32_16x16x32_bf16 v[32:35], v[156:159], v[172:175], v[32:35]
	v_mfma_f32_16x16x32_bf16 v[36:39], v[136:139], v[168:171], 0
	v_mfma_f32_16x16x32_bf16 v[36:39], v[148:151], v[172:175], v[36:39]
	v_mfma_f32_16x16x32_bf16 v[20:23], v[136:139], v[176:179], 0
	v_mfma_f32_16x16x32_bf16 v[20:23], v[148:151], v[180:183], v[20:23]
	v_mfma_f32_16x16x32_bf16 v[16:19], v[152:155], v[176:179], 0
	v_mfma_f32_16x16x32_bf16 v[16:19], v[156:159], v[180:183], v[16:19]
	v_mfma_f32_16x16x32_bf16 v[0:3], v[152:155], v[202:205], 0
	v_mfma_f32_16x16x32_bf16 v[0:3], v[156:159], v[228:231], v[0:3]
	v_mfma_f32_16x16x32_bf16 v[4:7], v[136:139], v[202:205], 0
	v_mfma_f32_16x16x32_bf16 v[4:7], v[148:151], v[228:231], v[4:7]
	s_setprio 0
	s_barrier
	s_add_i32 s58, 0, 0x18000
	s_add_i32 s59, 0, 0x1c000
	v_add_u32_e32 v124, s58, v211
	v_add_u32_e32 v156, s59, v211
	ds_read_b128 v[88:91], v124
	ds_read_b128 v[100:103], v124 offset:1024
	ds_read_b128 v[112:115], v124 offset:2048
	ds_read_b128 v[124:127], v124 offset:3072
	ds_read_b128 v[136:139], v156
	ds_read_b128 v[148:151], v156 offset:1024
	ds_read_b128 v[152:155], v156 offset:2048
	ds_read_b128 v[156:159], v156 offset:3072
	s_add_u32 s46, s46, 0x40000
	s_addc_u32 s47, s47, 0
	s_mov_b32 m0, s34
	v_lshl_add_u64 v[224:225], s[46:47], 0, v[184:185]
	ds_read_b128 v[160:163], v238 offset:32768
	ds_read_b128 v[164:167], v238 offset:33792
	ds_read_b128 v[168:171], v238 offset:34816
	ds_read_b128 v[172:175], v238 offset:35840
	ds_read_b128 v[176:179], v238 offset:36864
	ds_read_b128 v[180:183], v238 offset:37888
	ds_read_b128 v[202:205], v238 offset:38912
	ds_read_b128 v[228:231], v238 offset:39936
	global_load_lds_dwordx4 v[224:225], off
	v_lshl_add_u64 v[224:225], s[46:47], 0, v[188:189]
	s_mov_b32 m0, s35
	s_nop 0
	global_load_lds_dwordx4 v[224:225], off
	s_waitcnt vmcnt(8)
	s_waitcnt lgkmcnt(0)
	s_barrier
	s_setprio 1
	s_waitcnt lgkmcnt(0)
	v_mfma_f32_16x16x32_bf16 v[144:147], v[88:91], v[160:163], v[144:147]
	v_mfma_f32_16x16x32_bf16 v[144:147], v[100:103], v[164:167], v[144:147]
	v_mfma_f32_16x16x32_bf16 v[140:143], v[112:115], v[160:163], v[140:143]
	v_mfma_f32_16x16x32_bf16 v[140:143], v[124:127], v[164:167], v[140:143]
	v_mfma_f32_16x16x32_bf16 v[116:119], v[112:115], v[168:171], v[116:119]
	v_mfma_f32_16x16x32_bf16 v[116:119], v[124:127], v[172:175], v[116:119]
	v_mfma_f32_16x16x32_bf16 v[120:123], v[88:91], v[168:171], v[120:123]
	v_mfma_f32_16x16x32_bf16 v[120:123], v[100:103], v[172:175], v[120:123]
	v_mfma_f32_16x16x32_bf16 v[96:99], v[88:91], v[176:179], v[96:99]
	v_mfma_f32_16x16x32_bf16 v[96:99], v[100:103], v[180:183], v[96:99]
	v_mfma_f32_16x16x32_bf16 v[92:95], v[112:115], v[176:179], v[92:95]
	v_mfma_f32_16x16x32_bf16 v[92:95], v[124:127], v[180:183], v[92:95]
	v_mfma_f32_16x16x32_bf16 v[72:75], v[112:115], v[202:205], v[72:75]
	v_mfma_f32_16x16x32_bf16 v[72:75], v[124:127], v[228:231], v[72:75]
	v_mfma_f32_16x16x32_bf16 v[76:79], v[88:91], v[202:205], v[76:79]
	v_mfma_f32_16x16x32_bf16 v[76:79], v[100:103], v[228:231], v[76:79]
	s_setprio 0
	s_setprio 1
	v_mfma_f32_16x16x32_bf16 v[132:135], v[136:139], v[160:163], v[132:135]
	v_mfma_f32_16x16x32_bf16 v[132:135], v[148:151], v[164:167], v[132:135]
	v_mfma_f32_16x16x32_bf16 v[128:131], v[152:155], v[160:163], v[128:131]
	v_mfma_f32_16x16x32_bf16 v[128:131], v[156:159], v[164:167], v[128:131]
	v_mfma_f32_16x16x32_bf16 v[104:107], v[152:155], v[168:171], v[104:107]
	v_mfma_f32_16x16x32_bf16 v[104:107], v[156:159], v[172:175], v[104:107]
	v_mfma_f32_16x16x32_bf16 v[108:111], v[136:139], v[168:171], v[108:111]
	v_mfma_f32_16x16x32_bf16 v[108:111], v[148:151], v[172:175], v[108:111]
	v_mfma_f32_16x16x32_bf16 v[84:87], v[136:139], v[176:179], v[84:87]
	v_mfma_f32_16x16x32_bf16 v[84:87], v[148:151], v[180:183], v[84:87]
	v_mfma_f32_16x16x32_bf16 v[80:83], v[152:155], v[176:179], v[80:83]
	v_mfma_f32_16x16x32_bf16 v[80:83], v[156:159], v[180:183], v[80:83]
	v_mfma_f32_16x16x32_bf16 v[64:67], v[152:155], v[202:205], v[64:67]
	v_mfma_f32_16x16x32_bf16 v[64:67], v[156:159], v[228:231], v[64:67]
	v_mfma_f32_16x16x32_bf16 v[68:71], v[136:139], v[202:205], v[68:71]
	v_mfma_f32_16x16x32_bf16 v[68:71], v[148:151], v[228:231], v[68:71]
	s_setprio 0
	s_barrier
	s_add_i32 s46, s58, s2
	v_lshl_add_u64 v[208:209], v[208:209], 0, s[24:25]
	s_mov_b32 m0, s46
	ds_read_b128 v[160:163], v238 offset:49152
	ds_read_b128 v[164:167], v238 offset:50176
	ds_read_b128 v[168:171], v238 offset:51200
	ds_read_b128 v[172:175], v238 offset:52224
	ds_read_b128 v[176:179], v238 offset:53248
	ds_read_b128 v[180:183], v238 offset:54272
	ds_read_b128 v[202:205], v238 offset:55296
	ds_read_b128 v[228:231], v238 offset:56320
	global_load_lds_dwordx4 v[208:209], off
	s_add_i32 m0, s46, 0x2000
	s_add_u32 s44, s44, 0x40080
	v_lshl_add_u64 v[208:209], v[212:213], 0, s[24:25]
	s_addc_u32 s45, s45, 0
	s_add_i32 s46, s59, s2
	global_load_lds_dwordx4 v[208:209], off
	v_lshl_add_u64 v[208:209], s[44:45], 0, v[186:187]
	s_mov_b32 m0, s46
	s_nop 0
	global_load_lds_dwordx4 v[208:209], off
	v_lshl_add_u64 v[208:209], s[44:45], 0, v[190:191]
	s_add_i32 m0, s46, 0x2000
	s_nop 0
	global_load_lds_dwordx4 v[208:209], off
	v_lshl_add_u64 v[208:209], v[216:217], 0, s[24:25]
	s_mov_b32 m0, s49
	s_nop 0
	global_load_lds_dwordx4 v[208:209], off
	v_lshl_add_u64 v[208:209], v[220:221], 0, s[24:25]
	s_mov_b32 m0, s50
	s_nop 0
	global_load_lds_dwordx4 v[208:209], off
	s_waitcnt vmcnt(8)
	s_waitcnt lgkmcnt(0)
	s_barrier
	s_setprio 1
	s_waitcnt lgkmcnt(0)
	v_mfma_f32_16x16x32_bf16 v[60:63], v[88:91], v[160:163], v[60:63]
	v_mfma_f32_16x16x32_bf16 v[60:63], v[100:103], v[164:167], v[60:63]
	v_mfma_f32_16x16x32_bf16 v[56:59], v[112:115], v[160:163], v[56:59]
	v_mfma_f32_16x16x32_bf16 v[56:59], v[124:127], v[164:167], v[56:59]
	v_mfma_f32_16x16x32_bf16 v[40:43], v[112:115], v[168:171], v[40:43]
	v_mfma_f32_16x16x32_bf16 v[40:43], v[124:127], v[172:175], v[40:43]
	v_mfma_f32_16x16x32_bf16 v[44:47], v[88:91], v[168:171], v[44:47]
	v_mfma_f32_16x16x32_bf16 v[44:47], v[100:103], v[172:175], v[44:47]
	v_mfma_f32_16x16x32_bf16 v[28:31], v[88:91], v[176:179], v[28:31]
	v_mfma_f32_16x16x32_bf16 v[28:31], v[100:103], v[180:183], v[28:31]
	v_mfma_f32_16x16x32_bf16 v[24:27], v[112:115], v[176:179], v[24:27]
	v_mfma_f32_16x16x32_bf16 v[24:27], v[124:127], v[180:183], v[24:27]
	v_mfma_f32_16x16x32_bf16 v[8:11], v[112:115], v[202:205], v[8:11]
	v_mfma_f32_16x16x32_bf16 v[8:11], v[124:127], v[228:231], v[8:11]
	v_mfma_f32_16x16x32_bf16 v[12:15], v[88:91], v[202:205], v[12:15]
	v_mfma_f32_16x16x32_bf16 v[12:15], v[100:103], v[228:231], v[12:15]
	s_setprio 0
	s_setprio 1
	v_mfma_f32_16x16x32_bf16 v[52:55], v[136:139], v[160:163], v[52:55]
	v_mfma_f32_16x16x32_bf16 v[52:55], v[148:151], v[164:167], v[52:55]
	v_mfma_f32_16x16x32_bf16 v[48:51], v[152:155], v[160:163], v[48:51]
	v_mfma_f32_16x16x32_bf16 v[48:51], v[156:159], v[164:167], v[48:51]
	v_mfma_f32_16x16x32_bf16 v[32:35], v[152:155], v[168:171], v[32:35]
	v_mfma_f32_16x16x32_bf16 v[32:35], v[156:159], v[172:175], v[32:35]
	v_mfma_f32_16x16x32_bf16 v[36:39], v[136:139], v[168:171], v[36:39]
	v_mfma_f32_16x16x32_bf16 v[36:39], v[148:151], v[172:175], v[36:39]
	v_mfma_f32_16x16x32_bf16 v[20:23], v[136:139], v[176:179], v[20:23]
	v_mfma_f32_16x16x32_bf16 v[20:23], v[148:151], v[180:183], v[20:23]
	v_mfma_f32_16x16x32_bf16 v[16:19], v[152:155], v[176:179], v[16:19]
	v_mfma_f32_16x16x32_bf16 v[16:19], v[156:159], v[180:183], v[16:19]
	v_mfma_f32_16x16x32_bf16 v[0:3], v[152:155], v[202:205], v[0:3]
	v_mfma_f32_16x16x32_bf16 v[0:3], v[156:159], v[228:231], v[0:3]
	v_mfma_f32_16x16x32_bf16 v[4:7], v[136:139], v[202:205], v[4:7]
	v_mfma_f32_16x16x32_bf16 v[4:7], v[148:151], v[228:231], v[4:7]
	s_setprio 0
	s_barrier
	s_add_i32 s57, s57, 2
	s_add_u32 s42, s42, 0x100
	s_addc_u32 s43, s43, 0
	s_add_u32 s55, s55, 0x100
	s_addc_u32 s56, s56, 0

.LBB0_665:
	s_or_b64 exec, exec, s[42:43]
	s_andn2_b64 vcc, exec, s[8:9]
	s_mov_b64 s[8:9], -1
	s_cbranch_vccnz .LBB0_638
	s_andn2_b64 vcc, exec, s[22:23]
	s_cbranch_vccnz .LBB0_637
	s_mov_b32 s98, 1
	s_branch .LBB0_637

.LBB0_741:
	s_and_b32 s22, s18, 3
	s_mov_b64 s[18:19], 0x80
	s_add_i32 m0, s31, 0x18000
	v_lshl_add_u64 v[6:7], v[6:7], 0, s[18:19]
	s_lshl_b32 s1, s6, 13
	s_lshl_b32 s23, s22, 12
	s_waitcnt vmcnt(2)
	s_barrier
	global_load_lds_dwordx4 v[6:7], off
	v_lshl_add_u64 v[4:5], v[4:5], 0, s[18:19]
	s_add_i32 m0, s31, 0x1a000
	s_add_i32 s44, s31, 0x8000
	s_add_i32 s45, s31, 0xa000
	global_load_lds_dwordx4 v[4:5], off
	v_lshl_add_u64 v[0:1], v[0:1], 0, s[18:19]
	s_mov_b32 m0, s44
	s_add_u32 s20, s38, 0x40080
	global_load_lds_dwordx4 v[0:1], off
	v_lshl_add_u64 v[0:1], v[2:3], 0, s[18:19]
	s_mov_b32 m0, s45
	s_addc_u32 s21, s39, 0
	global_load_lds_dwordx4 v[0:1], off
	s_add_i32 m0, s31, 0x1c000
	v_lshl_add_u64 v[0:1], s[20:21], 0, v[132:133]
	global_load_lds_dwordx4 v[0:1], off
	v_lshl_add_u64 v[0:1], s[20:21], 0, v[128:129]
	s_add_i32 m0, s31, 0x1e000
	s_sext_i32_i8 s49, s0
	global_load_lds_dwordx4 v[0:1], off
	v_lshrrev_b32_e32 v1, 1, v8
	v_and_b32_e32 v1, 24, v1
	v_and_b32_e32 v0, 15, v8
	v_lshlrev_b32_e32 v2, 1, v1
	v_lshl_or_b32 v2, v0, 6, v2
	v_lshlrev_b32_e32 v0, 2, v0
	v_and_b32_e32 v3, 32, v0
	v_lshl_or_b32 v151, s22, 6, v1
	v_lshlrev_b32_e32 v1, 14, v13
	v_bitop3_b32 v4, v2, s1, v3 bitop3:0xde
	v_bitop3_b32 v148, v2, s23, v3 bitop3:0xde
	v_and_b32_e32 v2, 14, v8
	v_and_b32_e32 v1, 0xffff8000, v1
	v_lshl_or_b32 v150, s6, 6, v2
	v_lshl_add_u32 v1, v12, 11, v1
	v_and_b32_e32 v2, 1, v13
	s_lshl_b32 s0, s6, 8
	v_lshl_or_b32 v1, v2, 6, v1
	s_add_i32 s0, s0, 0
	v_lshl_add_u32 v138, v14, 1, v1
	v_lshlrev_b32_e32 v1, 14, v9
	s_add_i32 s0, s0, 0x20000
	v_and_b32_e32 v1, 0xffff8000, v1
	s_waitcnt vmcnt(6)
	v_add_u32_e32 v149, s0, v0
	s_cmpk_lt_u32 s7, 0x100
	v_and_b32_e32 v0, 1, v8
	v_lshl_add_u32 v1, v10, 11, v1
	v_and_b32_e32 v2, 1, v9
	s_cselect_b64 s[20:21], -1, 0
	v_cmp_eq_u32_e64 s[0:1], 0, v0
	v_lshlrev_b32_e32 v0, 5, v0
	v_lshl_or_b32 v1, v2, 6, v1
	s_add_i32 s47, 0, 0x10000
	s_add_i32 s48, 0, 0x14000
	s_mov_b32 s46, 0
	v_mov_b32_e32 v139, v137
	v_lshl_add_u32 v140, v11, 1, v1
	v_mov_b32_e32 v141, v137
	v_mov_b64_e32 v[142:143], 0x800
	v_mov_b64_e32 v[144:145], 0x7ff
	v_add_u32_e32 v152, s47, v148
	v_add_u32_e32 v153, s48, v148
	v_add_u32_e32 v154, 0, v4
	v_lshlrev_b32_e32 v136, 1, v0
	s_barrier
	s_waitcnt vmcnt(0)
	s_mov_b32 s98, 0
	s_branch .LBB0_744

.LBB0_750:
	s_ashr_i32 s25, s24, 31
	s_lshl_b64 s[26:27], s[24:25], 19
	s_add_u32 s26, s14, s26
	s_addc_u32 s27, s15, s27
	s_and_b64 s[28:29], s[6:7], exec
	s_cselect_b32 s25, s27, s37
	s_cselect_b32 s50, s26, s36
	s_ashr_i32 s23, s22, 31
	s_lshl_b64 s[28:29], s[22:23], 19
	s_add_u32 s28, s16, s28
	s_addc_u32 s29, s17, s29
	s_and_b64 s[40:41], s[6:7], exec
	s_cselect_b32 s23, s29, s39
	s_cselect_b32 s51, s28, s38
	s_add_u32 s36, s36, 0x40080
	s_addc_u32 s37, s37, 0
	s_add_u32 s52, s38, 0x100
	s_addc_u32 s53, s39, 0
	s_mov_b32 s54, -2
	s_cmp_eq_u32 s98, 0
	s_cbranch_scc1 .Ltb_skip_2
	s_barrier
	s_mov_b32 s98, 0
.Ltb_skip_2:
	ds_read_b128 v[156:159], v152
	ds_read_b128 v[160:163], v152 offset:1024
	ds_read_b128 v[164:167], v152 offset:2048
	ds_read_b128 v[168:171], v152 offset:3072
	ds_read_b128 v[172:175], v153
	ds_read_b128 v[176:179], v153 offset:1024
	ds_read_b128 v[180:183], v153 offset:2048
	ds_read_b128 v[184:187], v153 offset:3072
	s_add_u32 s38, s36, 0xfffc0080
	s_addc_u32 s39, s37, -1
	s_cmp_eq_u32 s54, 12
	s_cselect_b32 s41, s25, s39
	s_cselect_b32 s40, s50, s38
	s_cselect_b32 s39, s23, s53
	s_cselect_b32 s38, s51, s52
	v_lshl_add_u64 v[146:147], s[36:37], 0, v[138:139]
	s_add_i32 m0, s31, 0xc000
	ds_read_b128 v[188:191], v154
	ds_read_b128 v[192:195], v154 offset:1024
	ds_read_b128 v[196:199], v154 offset:2048
	ds_read_b128 v[200:203], v154 offset:3072
	ds_read_b128 v[204:207], v154 offset:4096
	ds_read_b128 v[208:211], v154 offset:5120
	ds_read_b128 v[216:219], v154 offset:6144
	ds_read_b128 v[220:223], v154 offset:7168
	global_load_lds_dwordx4 v[146:147], off
	v_lshl_add_u64 v[146:147], s[36:37], 0, v[140:141]
	s_add_i32 m0, s31, 0xe000
	s_nop 0
	global_load_lds_dwordx4 v[146:147], off
	s_waitcnt vmcnt(8)
	s_waitcnt lgkmcnt(0)
	s_barrier
	s_setprio 1
	s_waitcnt lgkmcnt(0)
	v_mfma_f32_16x16x32_bf16 v[124:127], v[156:159], v[188:191], 0
	v_mfma_f32_16x16x32_bf16 v[124:127], v[160:163], v[192:195], v[124:127]
	v_mfma_f32_16x16x32_bf16 v[120:123], v[164:167], v[188:191], 0
	v_mfma_f32_16x16x32_bf16 v[120:123], v[168:171], v[192:195], v[120:123]
	v_mfma_f32_16x16x32_bf16 v[104:107], v[164:167], v[196:199], 0
	v_mfma_f32_16x16x32_bf16 v[104:107], v[168:171], v[200:203], v[104:107]
	v_mfma_f32_16x16x32_bf16 v[108:111], v[156:159], v[196:199], 0
	v_mfma_f32_16x16x32_bf16 v[108:111], v[160:163], v[200:203], v[108:111]
	v_mfma_f32_16x16x32_bf16 v[92:95], v[156:159], v[204:207], 0
	v_mfma_f32_16x16x32_bf16 v[92:95], v[160:163], v[208:211], v[92:95]
	v_mfma_f32_16x16x32_bf16 v[88:91], v[164:167], v[204:207], 0
	v_mfma_f32_16x16x32_bf16 v[88:91], v[168:171], v[208:211], v[88:91]
	v_mfma_f32_16x16x32_bf16 v[72:75], v[164:167], v[216:219], 0
	v_mfma_f32_16x16x32_bf16 v[72:75], v[168:171], v[220:223], v[72:75]
	v_mfma_f32_16x16x32_bf16 v[76:79], v[156:159], v[216:219], 0
	v_mfma_f32_16x16x32_bf16 v[76:79], v[160:163], v[220:223], v[76:79]
	s_setprio 0
	s_setprio 1
	v_mfma_f32_16x16x32_bf16 v[116:119], v[172:175], v[188:191], 0
	v_mfma_f32_16x16x32_bf16 v[116:119], v[176:179], v[192:195], v[116:119]
	v_mfma_f32_16x16x32_bf16 v[112:115], v[180:183], v[188:191], 0
	v_mfma_f32_16x16x32_bf16 v[112:115], v[184:187], v[192:195], v[112:115]
	v_mfma_f32_16x16x32_bf16 v[96:99], v[180:183], v[196:199], 0
	v_mfma_f32_16x16x32_bf16 v[96:99], v[184:187], v[200:203], v[96:99]
	v_mfma_f32_16x16x32_bf16 v[100:103], v[172:175], v[196:199], 0
	v_mfma_f32_16x16x32_bf16 v[100:103], v[176:179], v[200:203], v[100:103]
	v_mfma_f32_16x16x32_bf16 v[84:87], v[172:175], v[204:207], 0
	v_mfma_f32_16x16x32_bf16 v[84:87], v[176:179], v[208:211], v[84:87]
	v_mfma_f32_16x16x32_bf16 v[80:83], v[180:183], v[204:207], 0
	v_mfma_f32_16x16x32_bf16 v[80:83], v[184:187], v[208:211], v[80:83]
	v_mfma_f32_16x16x32_bf16 v[64:67], v[180:183], v[216:219], 0
	v_mfma_f32_16x16x32_bf16 v[64:67], v[184:187], v[220:223], v[64:67]
	v_mfma_f32_16x16x32_bf16 v[68:71], v[172:175], v[216:219], 0
	v_mfma_f32_16x16x32_bf16 v[68:71], v[176:179], v[220:223], v[68:71]
	s_setprio 0
	s_barrier
	s_add_i32 s55, s47, s33
	v_lshl_add_u64 v[146:147], s[38:39], 0, v[132:133]
	s_mov_b32 m0, s55
	ds_read_b128 v[188:191], v154 offset:16384
	ds_read_b128 v[192:195], v154 offset:17408
	ds_read_b128 v[196:199], v154 offset:18432
	ds_read_b128 v[200:203], v154 offset:19456
	ds_read_b128 v[204:207], v154 offset:20480
	ds_read_b128 v[208:211], v154 offset:21504
	ds_read_b128 v[216:219], v154 offset:22528
	ds_read_b128 v[220:223], v154 offset:23552
	global_load_lds_dwordx4 v[146:147], off
	s_add_i32 m0, s55, 0x2000
	s_add_u32 s56, s38, 0x40000
	v_lshl_add_u64 v[212:213], s[38:39], 0, v[128:129]
	s_addc_u32 s57, s39, 0
	s_add_i32 s55, s48, s33
	global_load_lds_dwordx4 v[212:213], off
	v_lshl_add_u64 v[224:225], s[56:57], 0, v[132:133]
	s_mov_b32 m0, s55
	v_lshl_add_u64 v[226:227], s[40:41], 0, v[130:131]
	global_load_lds_dwordx4 v[224:225], off
	v_lshl_add_u64 v[224:225], s[56:57], 0, v[128:129]
	s_add_i32 m0, s55, 0x2000
	s_nop 0
	global_load_lds_dwordx4 v[224:225], off
	v_lshl_add_u64 v[224:225], s[40:41], 0, v[134:135]
	s_mov_b32 m0, s31
	s_nop 0
	global_load_lds_dwordx4 v[224:225], off
	s_mov_b32 m0, s34
	s_nop 0
	global_load_lds_dwordx4 v[226:227], off
	s_waitcnt vmcnt(8)
	s_waitcnt lgkmcnt(0)
	s_barrier
	s_setprio 1
	s_waitcnt lgkmcnt(0)
	v_mfma_f32_16x16x32_bf16 v[60:63], v[156:159], v[188:191], 0
	v_mfma_f32_16x16x32_bf16 v[60:63], v[160:163], v[192:195], v[60:63]
	v_mfma_f32_16x16x32_bf16 v[56:59], v[164:167], v[188:191], 0
	v_mfma_f32_16x16x32_bf16 v[56:59], v[168:171], v[192:195], v[56:59]
	v_mfma_f32_16x16x32_bf16 v[40:43], v[164:167], v[196:199], 0
	v_mfma_f32_16x16x32_bf16 v[40:43], v[168:171], v[200:203], v[40:43]
	v_mfma_f32_16x16x32_bf16 v[44:47], v[156:159], v[196:199], 0
	v_mfma_f32_16x16x32_bf16 v[44:47], v[160:163], v[200:203], v[44:47]
	v_mfma_f32_16x16x32_bf16 v[28:31], v[156:159], v[204:207], 0
	v_mfma_f32_16x16x32_bf16 v[28:31], v[160:163], v[208:211], v[28:31]
	v_mfma_f32_16x16x32_bf16 v[24:27], v[164:167], v[204:207], 0
	v_mfma_f32_16x16x32_bf16 v[24:27], v[168:171], v[208:211], v[24:27]
	v_mfma_f32_16x16x32_bf16 v[8:11], v[164:167], v[216:219], 0
	v_mfma_f32_16x16x32_bf16 v[8:11], v[168:171], v[220:223], v[8:11]
	v_mfma_f32_16x16x32_bf16 v[12:15], v[156:159], v[216:219], 0
	v_mfma_f32_16x16x32_bf16 v[12:15], v[160:163], v[220:223], v[12:15]
	s_setprio 0
	s_setprio 1
	v_mfma_f32_16x16x32_bf16 v[52:55], v[172:175], v[188:191], 0
	v_mfma_f32_16x16x32_bf16 v[52:55], v[176:179], v[192:195], v[52:55]
	v_mfma_f32_16x16x32_bf16 v[48:51], v[180:183], v[188:191], 0
	v_mfma_f32_16x16x32_bf16 v[48:51], v[184:187], v[192:195], v[48:51]
	v_mfma_f32_16x16x32_bf16 v[32:35], v[180:183], v[196:199], 0
	v_mfma_f32_16x16x32_bf16 v[32:35], v[184:187], v[200:203], v[32:35]
	v_mfma_f32_16x16x32_bf16 v[36:39], v[172:175], v[196:199], 0
	v_mfma_f32_16x16x32_bf16 v[36:39], v[176:179], v[200:203], v[36:39]
	v_mfma_f32_16x16x32_bf16 v[20:23], v[172:175], v[204:207], 0
	v_mfma_f32_16x16x32_bf16 v[20:23], v[176:179], v[208:211], v[20:23]
	v_mfma_f32_16x16x32_bf16 v[16:19], v[180:183], v[204:207], 0
	v_mfma_f32_16x16x32_bf16 v[16:19], v[184:187], v[208:211], v[16:19]
	v_mfma_f32_16x16x32_bf16 v[0:3], v[180:183], v[216:219], 0
	v_mfma_f32_16x16x32_bf16 v[0:3], v[184:187], v[220:223], v[0:3]
	v_mfma_f32_16x16x32_bf16 v[4:7], v[172:175], v[216:219], 0
	v_mfma_f32_16x16x32_bf16 v[4:7], v[176:179], v[220:223], v[4:7]
	s_setprio 0
	s_barrier
	s_add_i32 s55, 0, 0x18000
	v_add_u32_e32 v155, s55, v148
	s_add_i32 s56, 0, 0x1c000
	ds_read_b128 v[156:159], v155
	ds_read_b128 v[160:163], v155 offset:1024
	ds_read_b128 v[164:167], v155 offset:2048
	ds_read_b128 v[168:171], v155 offset:3072
	v_add_u32_e32 v155, s56, v148
	ds_read_b128 v[172:175], v155
	ds_read_b128 v[176:179], v155 offset:1024
	ds_read_b128 v[180:183], v155 offset:2048
	ds_read_b128 v[184:187], v155 offset:3072
	s_add_u32 s40, s40, 0x40000
	s_addc_u32 s41, s41, 0
	s_mov_b32 m0, s35
	v_lshl_add_u64 v[228:229], s[40:41], 0, v[134:135]
	ds_read_b128 v[188:191], v154 offset:32768
	ds_read_b128 v[192:195], v154 offset:33792
	ds_read_b128 v[196:199], v154 offset:34816
	ds_read_b128 v[200:203], v154 offset:35840
	ds_read_b128 v[204:207], v154 offset:36864
	ds_read_b128 v[208:211], v154 offset:37888
	ds_read_b128 v[216:219], v154 offset:38912
	ds_read_b128 v[220:223], v154 offset:39936
	global_load_lds_dwordx4 v[228:229], off
	v_lshl_add_u64 v[228:229], s[40:41], 0, v[130:131]
	s_mov_b32 m0, s42
	s_nop 0
	global_load_lds_dwordx4 v[228:229], off
	s_waitcnt vmcnt(8)
	s_waitcnt lgkmcnt(0)
	s_barrier
	s_setprio 1
	s_waitcnt lgkmcnt(0)
	v_mfma_f32_16x16x32_bf16 v[124:127], v[156:159], v[188:191], v[124:127]
	v_mfma_f32_16x16x32_bf16 v[124:127], v[160:163], v[192:195], v[124:127]
	v_mfma_f32_16x16x32_bf16 v[120:123], v[164:167], v[188:191], v[120:123]
	v_mfma_f32_16x16x32_bf16 v[120:123], v[168:171], v[192:195], v[120:123]
	v_mfma_f32_16x16x32_bf16 v[104:107], v[164:167], v[196:199], v[104:107]
	v_mfma_f32_16x16x32_bf16 v[104:107], v[168:171], v[200:203], v[104:107]
	v_mfma_f32_16x16x32_bf16 v[108:111], v[156:159], v[196:199], v[108:111]
	v_mfma_f32_16x16x32_bf16 v[108:111], v[160:163], v[200:203], v[108:111]
	v_mfma_f32_16x16x32_bf16 v[92:95], v[156:159], v[204:207], v[92:95]
	v_mfma_f32_16x16x32_bf16 v[92:95], v[160:163], v[208:211], v[92:95]
	v_mfma_f32_16x16x32_bf16 v[88:91], v[164:167], v[204:207], v[88:91]
	v_mfma_f32_16x16x32_bf16 v[88:91], v[168:171], v[208:211], v[88:91]
	v_mfma_f32_16x16x32_bf16 v[72:75], v[164:167], v[216:219], v[72:75]
	v_mfma_f32_16x16x32_bf16 v[72:75], v[168:171], v[220:223], v[72:75]
	v_mfma_f32_16x16x32_bf16 v[76:79], v[156:159], v[216:219], v[76:79]
	v_mfma_f32_16x16x32_bf16 v[76:79], v[160:163], v[220:223], v[76:79]
	s_setprio 0
	s_setprio 1
	v_mfma_f32_16x16x32_bf16 v[116:119], v[172:175], v[188:191], v[116:119]
	v_mfma_f32_16x16x32_bf16 v[116:119], v[176:179], v[192:195], v[116:119]
	v_mfma_f32_16x16x32_bf16 v[112:115], v[180:183], v[188:191], v[112:115]
	v_mfma_f32_16x16x32_bf16 v[112:115], v[184:187], v[192:195], v[112:115]
	v_mfma_f32_16x16x32_bf16 v[96:99], v[180:183], v[196:199], v[96:99]
	v_mfma_f32_16x16x32_bf16 v[96:99], v[184:187], v[200:203], v[96:99]
	v_mfma_f32_16x16x32_bf16 v[100:103], v[172:175], v[196:199], v[100:103]
	v_mfma_f32_16x16x32_bf16 v[100:103], v[176:179], v[200:203], v[100:103]
	v_mfma_f32_16x16x32_bf16 v[84:87], v[172:175], v[204:207], v[84:87]
	v_mfma_f32_16x16x32_bf16 v[84:87], v[176:179], v[208:211], v[84:87]
	v_mfma_f32_16x16x32_bf16 v[80:83], v[180:183], v[204:207], v[80:83]
	v_mfma_f32_16x16x32_bf16 v[80:83], v[184:187], v[208:211], v[80:83]
	v_mfma_f32_16x16x32_bf16 v[64:67], v[180:183], v[216:219], v[64:67]
	v_mfma_f32_16x16x32_bf16 v[64:67], v[184:187], v[220:223], v[64:67]
	v_mfma_f32_16x16x32_bf16 v[68:71], v[172:175], v[216:219], v[68:71]
	v_mfma_f32_16x16x32_bf16 v[68:71], v[176:179], v[220:223], v[68:71]
	s_setprio 0
	s_barrier
	s_add_i32 s40, s55, s33
	v_lshl_add_u64 v[146:147], v[146:147], 0, s[18:19]
	s_mov_b32 m0, s40
	ds_read_b128 v[188:191], v154 offset:49152
	ds_read_b128 v[192:195], v154 offset:50176
	ds_read_b128 v[196:199], v154 offset:51200
	ds_read_b128 v[200:203], v154 offset:52224
	ds_read_b128 v[204:207], v154 offset:53248
	ds_read_b128 v[208:211], v154 offset:54272
	ds_read_b128 v[216:219], v154 offset:55296
	ds_read_b128 v[220:223], v154 offset:56320
	global_load_lds_dwordx4 v[146:147], off
	s_add_i32 m0, s40, 0x2000
	s_add_u32 s38, s38, 0x40080
	v_lshl_add_u64 v[146:147], v[212:213], 0, s[18:19]
	s_addc_u32 s39, s39, 0
	s_add_i32 s40, s56, s33
	global_load_lds_dwordx4 v[146:147], off
	v_lshl_add_u64 v[146:147], s[38:39], 0, v[132:133]
	s_mov_b32 m0, s40
	s_nop 0
	global_load_lds_dwordx4 v[146:147], off
	v_lshl_add_u64 v[146:147], s[38:39], 0, v[128:129]
	s_add_i32 m0, s40, 0x2000
	s_nop 0
	global_load_lds_dwordx4 v[146:147], off
	v_lshl_add_u64 v[146:147], v[224:225], 0, s[18:19]
	s_mov_b32 m0, s44
	s_nop 0
	global_load_lds_dwordx4 v[146:147], off
	v_lshl_add_u64 v[146:147], v[226:227], 0, s[18:19]
	s_mov_b32 m0, s45
	s_nop 0
	global_load_lds_dwordx4 v[146:147], off
	s_waitcnt vmcnt(8)
	s_waitcnt lgkmcnt(0)
	s_barrier
	s_setprio 1
	s_waitcnt lgkmcnt(0)
	v_mfma_f32_16x16x32_bf16 v[60:63], v[156:159], v[188:191], v[60:63]
	v_mfma_f32_16x16x32_bf16 v[60:63], v[160:163], v[192:195], v[60:63]
	v_mfma_f32_16x16x32_bf16 v[56:59], v[164:167], v[188:191], v[56:59]
	v_mfma_f32_16x16x32_bf16 v[56:59], v[168:171], v[192:195], v[56:59]
	v_mfma_f32_16x16x32_bf16 v[40:43], v[164:167], v[196:199], v[40:43]
	v_mfma_f32_16x16x32_bf16 v[40:43], v[168:171], v[200:203], v[40:43]
	v_mfma_f32_16x16x32_bf16 v[44:47], v[156:159], v[196:199], v[44:47]
	v_mfma_f32_16x16x32_bf16 v[44:47], v[160:163], v[200:203], v[44:47]
	v_mfma_f32_16x16x32_bf16 v[28:31], v[156:159], v[204:207], v[28:31]
	v_mfma_f32_16x16x32_bf16 v[28:31], v[160:163], v[208:211], v[28:31]
	v_mfma_f32_16x16x32_bf16 v[24:27], v[164:167], v[204:207], v[24:27]
	v_mfma_f32_16x16x32_bf16 v[24:27], v[168:171], v[208:211], v[24:27]
	v_mfma_f32_16x16x32_bf16 v[8:11], v[164:167], v[216:219], v[8:11]
	v_mfma_f32_16x16x32_bf16 v[8:11], v[168:171], v[220:223], v[8:11]
	v_mfma_f32_16x16x32_bf16 v[12:15], v[156:159], v[216:219], v[12:15]
	v_mfma_f32_16x16x32_bf16 v[12:15], v[160:163], v[220:223], v[12:15]
	s_setprio 0
	s_setprio 1
	v_mfma_f32_16x16x32_bf16 v[52:55], v[172:175], v[188:191], v[52:55]
	v_mfma_f32_16x16x32_bf16 v[52:55], v[176:179], v[192:195], v[52:55]
	v_mfma_f32_16x16x32_bf16 v[48:51], v[180:183], v[188:191], v[48:51]
	v_mfma_f32_16x16x32_bf16 v[48:51], v[184:187], v[192:195], v[48:51]
	v_mfma_f32_16x16x32_bf16 v[32:35], v[180:183], v[196:199], v[32:35]
	v_mfma_f32_16x16x32_bf16 v[32:35], v[184:187], v[200:203], v[32:35]
	v_mfma_f32_16x16x32_bf16 v[36:39], v[172:175], v[196:199], v[36:39]
	v_mfma_f32_16x16x32_bf16 v[36:39], v[176:179], v[200:203], v[36:39]
	v_mfma_f32_16x16x32_bf16 v[20:23], v[172:175], v[204:207], v[20:23]
	v_mfma_f32_16x16x32_bf16 v[20:23], v[176:179], v[208:211], v[20:23]
	v_mfma_f32_16x16x32_bf16 v[16:19], v[180:183], v[204:207], v[16:19]
	v_mfma_f32_16x16x32_bf16 v[16:19], v[184:187], v[208:211], v[16:19]
	v_mfma_f32_16x16x32_bf16 v[0:3], v[180:183], v[216:219], v[0:3]
	v_mfma_f32_16x16x32_bf16 v[0:3], v[184:187], v[220:223], v[0:3]
	v_mfma_f32_16x16x32_bf16 v[4:7], v[172:175], v[216:219], v[4:7]
	v_mfma_f32_16x16x32_bf16 v[4:7], v[176:179], v[220:223], v[4:7]
	s_setprio 0
	s_barrier
	s_add_i32 s54, s54, 2
	s_add_u32 s36, s36, 0x100
	s_addc_u32 s37, s37, 0
	s_add_u32 s52, s52, 0x100
	s_addc_u32 s53, s53, 0

.LBB0_754:
	s_lshl_b32 s23, s30, 8
	s_and_b32 s25, s23, 0xc00
	v_add_u32_e32 v155, s25, v149
	ds_read_b32 v156, v155
	v_add_u32_e32 v146, s23, v150
	v_lshl_or_b32 v158, s49, 8, v151
	v_ashrrev_i32_e32 v147, 31, v146
	v_ashrrev_i32_e32 v159, 31, v158
	s_waitcnt lgkmcnt(0)
	v_pk_mul_f32 v[126:127], v[126:127], v[156:157] op_sel_hi:[1,0]
	v_pk_mul_f32 v[124:125], v[124:125], v[156:157] op_sel_hi:[1,0]
	v_pk_mul_f32 v[122:123], v[122:123], v[156:157] op_sel_hi:[1,0]
	v_pk_mul_f32 v[120:121], v[120:121], v[156:157] op_sel_hi:[1,0]
	v_pk_mul_f32 v[114:115], v[114:115], v[156:157] op_sel_hi:[1,0]
	v_max_f32_e32 v124, 0, v124
	v_max_f32_e32 v120, 0, v120
	v_max_f32_e32 v125, 0, v125
	v_max_f32_e32 v121, 0, v121
	v_max_f32_e32 v126, 0, v126
	v_max_f32_e32 v122, 0, v122
	v_max_f32_e32 v127, 0, v127
	v_max_f32_e32 v123, 0, v123
	v_pk_mul_f32 v[118:119], v[118:119], v[156:157] op_sel_hi:[1,0]
	v_pk_mul_f32 v[116:117], v[116:117], v[156:157] op_sel_hi:[1,0]
	v_pk_mul_f32 v[112:113], v[112:113], v[156:157] op_sel_hi:[1,0]
	v_max_f32_e32 v114, 0, v114
	v_mul_f32_e32 v124, v124, v124
	v_mul_f32_e32 v120, v120, v120
	v_mul_f32_e32 v125, v125, v125
	v_mul_f32_e32 v121, v121, v121
	v_mul_f32_e32 v126, v126, v126
	v_mul_f32_e32 v122, v122, v122
	v_mul_f32_e32 v127, v127, v127
	v_mul_f32_e32 v123, v123, v123
	v_max_f32_e32 v116, 0, v116
	v_max_f32_e32 v112, 0, v112
	v_max_f32_e32 v117, 0, v117
	v_max_f32_e32 v113, 0, v113
	v_max_f32_e32 v118, 0, v118
	v_mul_f32_e32 v114, v114, v114
	v_max_f32_e32 v119, 0, v119
	v_max_f32_e32 v115, 0, v115
	v_cvt_pk_bf16_f32 v124, v124, v125
	v_cvt_pk_bf16_f32 v125, v126, v127
	v_cvt_pk_bf16_f32 v120, v120, v121
	v_cvt_pk_bf16_f32 v121, v122, v123
	v_mul_f32_e32 v116, v116, v116
	v_mul_f32_e32 v112, v112, v112
	v_mul_f32_e32 v117, v117, v117
	v_mul_f32_e32 v113, v113, v113
	v_mul_f32_e32 v118, v118, v118
	v_mul_f32_e32 v119, v119, v119
	v_mul_f32_e32 v115, v115, v115
	v_cvt_pk_bf16_f32 v122, v116, v117
	v_cvt_pk_bf16_f32 v123, v118, v119
	v_cvt_pk_bf16_f32 v126, v112, v113
	v_cvt_pk_bf16_f32 v127, v114, v115
	s_nop 0
	v_cndmask_b32_e64 v114, v120, v126, s[0:1]
	v_cndmask_b32_e64 v112, v121, v127, s[0:1]
	v_cndmask_b32_e64 v113, v125, v123, s[0:1]
	v_mov_b32_dpp v160, v114 quad_perm:[1,0,3,2] row_mask:0xf bank_mask:0xf bound_ctrl:1
	v_cndmask_b32_e64 v116, v160, v120, s[0:1]
	ds_read_b32 v120, v155 offset:64
	v_cndmask_b32_e64 v115, v124, v122, s[0:1]
	v_mov_b32_dpp v157, v113 quad_perm:[1,0,3,2] row_mask:0xf bank_mask:0xf bound_ctrl:1
	v_mov_b32_dpp v161, v112 quad_perm:[1,0,3,2] row_mask:0xf bank_mask:0xf bound_ctrl:1
	v_lshlrev_b64 v[112:113], 13, v[146:147]
	v_mov_b32_dpp v156, v115 quad_perm:[1,0,3,2] row_mask:0xf bank_mask:0xf bound_ctrl:1
	v_lshl_add_u64 v[114:115], s[60:61], 0, v[112:113]
	v_lshlrev_b64 v[112:113], 1, v[158:159]
	v_lshl_add_u64 v[114:115], v[114:115], 0, v[112:113]
	v_lshl_add_u64 v[118:119], v[114:115], 0, v[136:137]
	v_cndmask_b32_e64 v115, v157, v125, s[0:1]
	v_cndmask_b32_e64 v117, v161, v121, s[0:1]
	v_cndmask_b32_e64 v114, v156, v124, s[0:1]
	s_waitcnt lgkmcnt(0)
	v_pk_mul_f32 v[108:109], v[108:109], v[120:121] op_sel_hi:[1,0]
	v_pk_mul_f32 v[106:107], v[106:107], v[120:121] op_sel_hi:[1,0]
	v_pk_mul_f32 v[104:105], v[104:105], v[120:121] op_sel_hi:[1,0]
	v_pk_mul_f32 v[102:103], v[102:103], v[120:121] op_sel_hi:[1,0]
	v_pk_mul_f32 v[96:97], v[96:97], v[120:121] op_sel_hi:[1,0]
	global_store_dwordx4 v[118:119], v[114:117], off nt
	v_add_co_u32_e32 v118, vcc, s43, v118
	v_pk_mul_f32 v[110:111], v[110:111], v[120:121] op_sel_hi:[1,0]
	v_max_f32_e32 v108, 0, v108
	v_max_f32_e32 v104, 0, v104
	v_max_f32_e32 v109, 0, v109
	v_max_f32_e32 v105, 0, v105
	v_max_f32_e32 v106, 0, v106
	v_max_f32_e32 v107, 0, v107
	v_pk_mul_f32 v[100:101], v[100:101], v[120:121] op_sel_hi:[1,0]
	v_pk_mul_f32 v[98:99], v[98:99], v[120:121] op_sel_hi:[1,0]
	v_max_f32_e32 v96, 0, v96
	v_max_f32_e32 v97, 0, v97
	v_max_f32_e32 v102, 0, v102
	v_max_f32_e32 v103, 0, v103
	v_cndmask_b32_e64 v115, v123, v157, s[0:1]
	v_cndmask_b32_e64 v117, v127, v161, s[0:1]
	v_cndmask_b32_e64 v114, v122, v156, s[0:1]
	v_cndmask_b32_e64 v116, v126, v160, s[0:1]
	v_addc_co_u32_e32 v119, vcc, 0, v119, vcc
	v_mul_f32_e32 v108, v108, v108
	v_mul_f32_e32 v104, v104, v104
	v_mul_f32_e32 v109, v109, v109
	v_mul_f32_e32 v105, v105, v105
	v_max_f32_e32 v110, 0, v110
	v_mul_f32_e32 v106, v106, v106
	v_max_f32_e32 v111, 0, v111
	v_mul_f32_e32 v107, v107, v107
	v_max_f32_e32 v100, 0, v100
	v_mul_f32_e32 v96, v96, v96
	v_max_f32_e32 v101, 0, v101
	v_mul_f32_e32 v97, v97, v97
	v_max_f32_e32 v98, 0, v98
	v_mul_f32_e32 v102, v102, v102
	v_max_f32_e32 v99, 0, v99
	v_mul_f32_e32 v103, v103, v103
	global_store_dwordx4 v[118:119], v[114:117], off nt
	v_mul_f32_e32 v110, v110, v110
	v_mul_f32_e32 v111, v111, v111
	v_cvt_pk_bf16_f32 v108, v108, v109
	v_cvt_pk_bf16_f32 v109, v110, v111
	v_cvt_pk_bf16_f32 v104, v104, v105
	v_cvt_pk_bf16_f32 v105, v106, v107
	v_mul_f32_e32 v100, v100, v100
	v_mul_f32_e32 v101, v101, v101
	v_mul_f32_e32 v98, v98, v98
	v_mul_f32_e32 v99, v99, v99
	v_cvt_pk_bf16_f32 v106, v100, v101
	v_cvt_pk_bf16_f32 v102, v102, v103
	v_cvt_pk_bf16_f32 v103, v96, v97
	v_cvt_pk_bf16_f32 v107, v98, v99
	v_or_b32_e32 v96, 16, v146
	v_cndmask_b32_e64 v97, v105, v107, s[0:1]
	v_cndmask_b32_e64 v98, v109, v102, s[0:1]
	v_cndmask_b32_e64 v99, v104, v103, s[0:1]
	v_mov_b32_dpp v115, v97 quad_perm:[1,0,3,2] row_mask:0xf bank_mask:0xf bound_ctrl:1
	v_ashrrev_i32_e32 v97, 31, v96
	v_lshlrev_b64 v[96:97], 13, v[96:97]
	v_cndmask_b32_e64 v100, v108, v106, s[0:1]
	v_lshl_add_u64 v[96:97], s[60:61], 0, v[96:97]
	v_mov_b32_dpp v111, v98 quad_perm:[1,0,3,2] row_mask:0xf bank_mask:0xf bound_ctrl:1
	v_mov_b32_dpp v110, v100 quad_perm:[1,0,3,2] row_mask:0xf bank_mask:0xf bound_ctrl:1
	v_mov_b32_dpp v114, v99 quad_perm:[1,0,3,2] row_mask:0xf bank_mask:0xf bound_ctrl:1
	v_lshl_add_u64 v[96:97], v[96:97], 0, v[112:113]
	v_lshl_add_u64 v[100:101], v[96:97], 0, v[136:137]
	v_cndmask_b32_e64 v97, v111, v109, s[0:1]
	v_cndmask_b32_e64 v99, v115, v105, s[0:1]
	v_cndmask_b32_e64 v96, v110, v108, s[0:1]
	v_cndmask_b32_e64 v98, v114, v104, s[0:1]
	global_store_dwordx4 v[100:101], v[96:99], off nt
	v_add_co_u32_e32 v100, vcc, s43, v100
	s_nop 0
	v_cndmask_b32_e64 v97, v102, v111, s[0:1]
	ds_read_b32 v102, v155 offset:128
	v_cndmask_b32_e64 v99, v107, v115, s[0:1]
	v_cndmask_b32_e64 v96, v106, v110, s[0:1]
	v_cndmask_b32_e64 v98, v103, v114, s[0:1]
	v_addc_co_u32_e32 v101, vcc, 0, v101, vcc
	s_waitcnt lgkmcnt(0)
	v_pk_mul_f32 v[92:93], v[92:93], v[102:103] op_sel_hi:[1,0]
	v_pk_mul_f32 v[90:91], v[90:91], v[102:103] op_sel_hi:[1,0]
	v_pk_mul_f32 v[88:89], v[88:89], v[102:103] op_sel_hi:[1,0]
	v_pk_mul_f32 v[86:87], v[86:87], v[102:103] op_sel_hi:[1,0]
	v_pk_mul_f32 v[80:81], v[80:81], v[102:103] op_sel_hi:[1,0]
	v_pk_mul_f32 v[94:95], v[94:95], v[102:103] op_sel_hi:[1,0]
	v_max_f32_e32 v92, 0, v92
	v_max_f32_e32 v88, 0, v88
	v_max_f32_e32 v93, 0, v93
	v_max_f32_e32 v89, 0, v89
	v_max_f32_e32 v90, 0, v90
	v_max_f32_e32 v91, 0, v91
	v_pk_mul_f32 v[84:85], v[84:85], v[102:103] op_sel_hi:[1,0]
	v_pk_mul_f32 v[82:83], v[82:83], v[102:103] op_sel_hi:[1,0]
	v_max_f32_e32 v80, 0, v80
	v_max_f32_e32 v81, 0, v81
	v_max_f32_e32 v86, 0, v86
	v_max_f32_e32 v87, 0, v87
	v_mul_f32_e32 v92, v92, v92
	v_mul_f32_e32 v88, v88, v88
	v_mul_f32_e32 v93, v93, v93
	v_mul_f32_e32 v89, v89, v89
	v_max_f32_e32 v94, 0, v94
	v_mul_f32_e32 v90, v90, v90
	v_max_f32_e32 v95, 0, v95
	v_mul_f32_e32 v91, v91, v91
	v_max_f32_e32 v84, 0, v84
	v_mul_f32_e32 v80, v80, v80
	v_max_f32_e32 v85, 0, v85
	v_mul_f32_e32 v81, v81, v81
	v_max_f32_e32 v82, 0, v82
	v_mul_f32_e32 v86, v86, v86
	v_max_f32_e32 v83, 0, v83
	v_mul_f32_e32 v87, v87, v87
	global_store_dwordx4 v[100:101], v[96:99], off nt
	v_mul_f32_e32 v94, v94, v94
	v_mul_f32_e32 v95, v95, v95
	v_cvt_pk_bf16_f32 v92, v92, v93
	v_cvt_pk_bf16_f32 v93, v94, v95
	v_cvt_pk_bf16_f32 v88, v88, v89
	v_cvt_pk_bf16_f32 v89, v90, v91
	v_mul_f32_e32 v84, v84, v84
	v_mul_f32_e32 v85, v85, v85
	v_mul_f32_e32 v82, v82, v82
	v_mul_f32_e32 v83, v83, v83
	v_cvt_pk_bf16_f32 v90, v84, v85
	v_cvt_pk_bf16_f32 v86, v86, v87
	v_cvt_pk_bf16_f32 v87, v80, v81
	v_cvt_pk_bf16_f32 v91, v82, v83
	v_or_b32_e32 v80, 32, v146
	v_cndmask_b32_e64 v81, v89, v91, s[0:1]
	v_cndmask_b32_e64 v82, v93, v86, s[0:1]
	v_cndmask_b32_e64 v83, v88, v87, s[0:1]
	v_mov_b32_dpp v97, v81 quad_perm:[1,0,3,2] row_mask:0xf bank_mask:0xf bound_ctrl:1
	v_ashrrev_i32_e32 v81, 31, v80
	v_lshlrev_b64 v[80:81], 13, v[80:81]
	v_cndmask_b32_e64 v84, v92, v90, s[0:1]
	v_lshl_add_u64 v[80:81], s[60:61], 0, v[80:81]
	v_mov_b32_dpp v95, v82 quad_perm:[1,0,3,2] row_mask:0xf bank_mask:0xf bound_ctrl:1
	v_mov_b32_dpp v94, v84 quad_perm:[1,0,3,2] row_mask:0xf bank_mask:0xf bound_ctrl:1
	v_mov_b32_dpp v96, v83 quad_perm:[1,0,3,2] row_mask:0xf bank_mask:0xf bound_ctrl:1
	v_lshl_add_u64 v[80:81], v[80:81], 0, v[112:113]
	v_lshl_add_u64 v[84:85], v[80:81], 0, v[136:137]
	v_cndmask_b32_e64 v81, v95, v93, s[0:1]
	v_cndmask_b32_e64 v83, v97, v89, s[0:1]
	v_cndmask_b32_e64 v80, v94, v92, s[0:1]
	v_cndmask_b32_e64 v82, v96, v88, s[0:1]
	global_store_dwordx4 v[84:85], v[80:83], off nt
	v_add_co_u32_e32 v84, vcc, s43, v84
	s_nop 0
	v_cndmask_b32_e64 v81, v86, v95, s[0:1]
	ds_read_b32 v86, v155 offset:192
	v_cndmask_b32_e64 v83, v91, v97, s[0:1]
	v_cndmask_b32_e64 v80, v90, v94, s[0:1]
	v_cndmask_b32_e64 v82, v87, v96, s[0:1]
	v_addc_co_u32_e32 v85, vcc, 0, v85, vcc
	s_waitcnt lgkmcnt(0)
	v_pk_mul_f32 v[76:77], v[76:77], v[86:87] op_sel_hi:[1,0]
	v_pk_mul_f32 v[74:75], v[74:75], v[86:87] op_sel_hi:[1,0]
	v_pk_mul_f32 v[72:73], v[72:73], v[86:87] op_sel_hi:[1,0]
	v_pk_mul_f32 v[70:71], v[70:71], v[86:87] op_sel_hi:[1,0]
	v_pk_mul_f32 v[64:65], v[64:65], v[86:87] op_sel_hi:[1,0]
	v_pk_mul_f32 v[78:79], v[78:79], v[86:87] op_sel_hi:[1,0]
	v_max_f32_e32 v76, 0, v76
	v_max_f32_e32 v72, 0, v72
	v_max_f32_e32 v77, 0, v77
	v_max_f32_e32 v73, 0, v73
	v_max_f32_e32 v74, 0, v74
	v_max_f32_e32 v75, 0, v75
	v_pk_mul_f32 v[68:69], v[68:69], v[86:87] op_sel_hi:[1,0]
	v_pk_mul_f32 v[66:67], v[66:67], v[86:87] op_sel_hi:[1,0]
	v_max_f32_e32 v64, 0, v64
	v_max_f32_e32 v65, 0, v65
	v_max_f32_e32 v70, 0, v70
	v_max_f32_e32 v71, 0, v71
	v_mul_f32_e32 v76, v76, v76
	v_mul_f32_e32 v72, v72, v72
	v_mul_f32_e32 v77, v77, v77
	v_mul_f32_e32 v73, v73, v73
	v_max_f32_e32 v78, 0, v78
	v_mul_f32_e32 v74, v74, v74
	v_max_f32_e32 v79, 0, v79
	v_mul_f32_e32 v75, v75, v75
	v_max_f32_e32 v68, 0, v68
	v_mul_f32_e32 v64, v64, v64
	v_max_f32_e32 v69, 0, v69
	v_mul_f32_e32 v65, v65, v65
	v_max_f32_e32 v66, 0, v66
	v_mul_f32_e32 v70, v70, v70
	v_max_f32_e32 v67, 0, v67
	v_mul_f32_e32 v71, v71, v71
	global_store_dwordx4 v[84:85], v[80:83], off nt
	v_mul_f32_e32 v78, v78, v78
	v_mul_f32_e32 v79, v79, v79
	v_cvt_pk_bf16_f32 v76, v76, v77
	v_cvt_pk_bf16_f32 v77, v78, v79
	v_cvt_pk_bf16_f32 v72, v72, v73
	v_cvt_pk_bf16_f32 v73, v74, v75
	v_mul_f32_e32 v68, v68, v68
	v_mul_f32_e32 v69, v69, v69
	v_mul_f32_e32 v66, v66, v66
	v_mul_f32_e32 v67, v67, v67
	v_cvt_pk_bf16_f32 v74, v68, v69
	v_cvt_pk_bf16_f32 v70, v70, v71
	v_cvt_pk_bf16_f32 v71, v64, v65
	v_cvt_pk_bf16_f32 v75, v66, v67
	v_or_b32_e32 v64, 48, v146
	v_cndmask_b32_e64 v65, v73, v75, s[0:1]
	v_cndmask_b32_e64 v66, v77, v70, s[0:1]
	v_cndmask_b32_e64 v67, v72, v71, s[0:1]
	v_mov_b32_dpp v81, v65 quad_perm:[1,0,3,2] row_mask:0xf bank_mask:0xf bound_ctrl:1
	v_ashrrev_i32_e32 v65, 31, v64
	v_lshlrev_b64 v[64:65], 13, v[64:65]
	v_cndmask_b32_e64 v68, v76, v74, s[0:1]
	v_lshl_add_u64 v[64:65], s[60:61], 0, v[64:65]
	v_mov_b32_dpp v79, v66 quad_perm:[1,0,3,2] row_mask:0xf bank_mask:0xf bound_ctrl:1
	v_mov_b32_dpp v78, v68 quad_perm:[1,0,3,2] row_mask:0xf bank_mask:0xf bound_ctrl:1
	v_mov_b32_dpp v80, v67 quad_perm:[1,0,3,2] row_mask:0xf bank_mask:0xf bound_ctrl:1
	v_lshl_add_u64 v[64:65], v[64:65], 0, v[112:113]
	v_lshl_add_u64 v[68:69], v[64:65], 0, v[136:137]
	v_cndmask_b32_e64 v65, v79, v77, s[0:1]
	v_cndmask_b32_e64 v67, v81, v73, s[0:1]
	v_cndmask_b32_e64 v64, v78, v76, s[0:1]
	v_cndmask_b32_e64 v66, v80, v72, s[0:1]
	global_store_dwordx4 v[68:69], v[64:67], off nt
	v_add_co_u32_e32 v68, vcc, s43, v68
	s_nop 0
	v_cndmask_b32_e64 v65, v70, v79, s[0:1]
	ds_read_b32 v70, v155 offset:512
	v_cndmask_b32_e64 v67, v75, v81, s[0:1]
	v_cndmask_b32_e64 v64, v74, v78, s[0:1]
	v_cndmask_b32_e64 v66, v71, v80, s[0:1]
	v_addc_co_u32_e32 v69, vcc, 0, v69, vcc
	s_waitcnt lgkmcnt(0)
	v_pk_mul_f32 v[60:61], v[60:61], v[70:71] op_sel_hi:[1,0]
	v_pk_mul_f32 v[58:59], v[58:59], v[70:71] op_sel_hi:[1,0]
	v_pk_mul_f32 v[56:57], v[56:57], v[70:71] op_sel_hi:[1,0]
	v_pk_mul_f32 v[54:55], v[54:55], v[70:71] op_sel_hi:[1,0]
	v_pk_mul_f32 v[48:49], v[48:49], v[70:71] op_sel_hi:[1,0]
	v_pk_mul_f32 v[62:63], v[62:63], v[70:71] op_sel_hi:[1,0]
	v_max_f32_e32 v60, 0, v60
	v_max_f32_e32 v56, 0, v56
	v_max_f32_e32 v61, 0, v61
	v_max_f32_e32 v57, 0, v57
	v_max_f32_e32 v58, 0, v58
	v_max_f32_e32 v59, 0, v59
	v_pk_mul_f32 v[52:53], v[52:53], v[70:71] op_sel_hi:[1,0]
	v_pk_mul_f32 v[50:51], v[50:51], v[70:71] op_sel_hi:[1,0]
	v_max_f32_e32 v48, 0, v48
	v_max_f32_e32 v49, 0, v49
	v_max_f32_e32 v54, 0, v54
	v_max_f32_e32 v55, 0, v55
	global_store_dwordx4 v[68:69], v[64:67], off nt
	v_mul_f32_e32 v60, v60, v60
	v_mul_f32_e32 v56, v56, v56
	v_add_u32_e32 v64, 0x80, v146
	v_mul_f32_e32 v61, v61, v61
	v_mul_f32_e32 v57, v57, v57
	v_max_f32_e32 v62, 0, v62
	v_mul_f32_e32 v58, v58, v58
	v_max_f32_e32 v63, 0, v63
	v_mul_f32_e32 v59, v59, v59
	v_max_f32_e32 v52, 0, v52
	v_mul_f32_e32 v48, v48, v48
	v_max_f32_e32 v53, 0, v53
	v_mul_f32_e32 v49, v49, v49
	v_max_f32_e32 v50, 0, v50
	v_mul_f32_e32 v54, v54, v54
	v_max_f32_e32 v51, 0, v51
	v_mul_f32_e32 v55, v55, v55
	v_mul_f32_e32 v62, v62, v62
	v_mul_f32_e32 v63, v63, v63
	v_cvt_pk_bf16_f32 v60, v60, v61
	v_cvt_pk_bf16_f32 v61, v62, v63
	v_cvt_pk_bf16_f32 v56, v56, v57
	v_cvt_pk_bf16_f32 v57, v58, v59
	v_mul_f32_e32 v52, v52, v52
	v_mul_f32_e32 v53, v53, v53
	v_mul_f32_e32 v50, v50, v50
	v_mul_f32_e32 v51, v51, v51
	v_cvt_pk_bf16_f32 v58, v52, v53
	v_cvt_pk_bf16_f32 v54, v54, v55
	v_cvt_pk_bf16_f32 v55, v48, v49
	v_cvt_pk_bf16_f32 v59, v50, v51
	v_ashrrev_i32_e32 v65, 31, v64
	v_cndmask_b32_e64 v48, v57, v59, s[0:1]
	v_cndmask_b32_e64 v49, v61, v54, s[0:1]
	v_cndmask_b32_e64 v50, v56, v55, s[0:1]
	v_mov_b32_dpp v67, v48 quad_perm:[1,0,3,2] row_mask:0xf bank_mask:0xf bound_ctrl:1
	v_mov_b32_dpp v63, v49 quad_perm:[1,0,3,2] row_mask:0xf bank_mask:0xf bound_ctrl:1
	v_lshlrev_b64 v[48:49], 13, v[64:65]
	v_cndmask_b32_e64 v51, v60, v58, s[0:1]
	v_lshl_add_u64 v[48:49], s[60:61], 0, v[48:49]
	v_mov_b32_dpp v66, v50 quad_perm:[1,0,3,2] row_mask:0xf bank_mask:0xf bound_ctrl:1
	v_mov_b32_dpp v62, v51 quad_perm:[1,0,3,2] row_mask:0xf bank_mask:0xf bound_ctrl:1
	v_lshl_add_u64 v[48:49], v[48:49], 0, v[112:113]
	v_lshl_add_u64 v[52:53], v[48:49], 0, v[136:137]
	v_cndmask_b32_e64 v49, v63, v61, s[0:1]
	v_cndmask_b32_e64 v51, v67, v57, s[0:1]
	v_cndmask_b32_e64 v48, v62, v60, s[0:1]
	v_cndmask_b32_e64 v50, v66, v56, s[0:1]
	global_store_dwordx4 v[52:53], v[48:51], off nt
	v_add_co_u32_e32 v52, vcc, s43, v52
	s_nop 0
	v_cndmask_b32_e64 v49, v54, v63, s[0:1]
	ds_read_b32 v54, v155 offset:576
	v_cndmask_b32_e64 v51, v59, v67, s[0:1]
	v_cndmask_b32_e64 v48, v58, v62, s[0:1]
	v_cndmask_b32_e64 v50, v55, v66, s[0:1]
	v_addc_co_u32_e32 v53, vcc, 0, v53, vcc
	s_waitcnt lgkmcnt(0)
	v_pk_mul_f32 v[44:45], v[44:45], v[54:55] op_sel_hi:[1,0]
	v_pk_mul_f32 v[42:43], v[42:43], v[54:55] op_sel_hi:[1,0]
	v_pk_mul_f32 v[40:41], v[40:41], v[54:55] op_sel_hi:[1,0]
	v_pk_mul_f32 v[38:39], v[38:39], v[54:55] op_sel_hi:[1,0]
	v_pk_mul_f32 v[32:33], v[32:33], v[54:55] op_sel_hi:[1,0]
	v_pk_mul_f32 v[46:47], v[46:47], v[54:55] op_sel_hi:[1,0]
	v_max_f32_e32 v44, 0, v44
	v_max_f32_e32 v40, 0, v40
	v_max_f32_e32 v45, 0, v45
	v_max_f32_e32 v41, 0, v41
	v_max_f32_e32 v42, 0, v42
	v_max_f32_e32 v43, 0, v43
	v_pk_mul_f32 v[36:37], v[36:37], v[54:55] op_sel_hi:[1,0]
	v_pk_mul_f32 v[34:35], v[34:35], v[54:55] op_sel_hi:[1,0]
	v_max_f32_e32 v32, 0, v32
	v_max_f32_e32 v33, 0, v33
	v_max_f32_e32 v38, 0, v38
	v_max_f32_e32 v39, 0, v39
	v_mul_f32_e32 v44, v44, v44
	v_mul_f32_e32 v40, v40, v40
	v_mul_f32_e32 v45, v45, v45
	v_mul_f32_e32 v41, v41, v41
	v_max_f32_e32 v46, 0, v46
	v_mul_f32_e32 v42, v42, v42
	v_max_f32_e32 v47, 0, v47
	v_mul_f32_e32 v43, v43, v43
	v_max_f32_e32 v36, 0, v36
	v_mul_f32_e32 v32, v32, v32
	v_max_f32_e32 v37, 0, v37
	v_mul_f32_e32 v33, v33, v33
	v_max_f32_e32 v34, 0, v34
	v_mul_f32_e32 v38, v38, v38
	v_max_f32_e32 v35, 0, v35
	v_mul_f32_e32 v39, v39, v39
	global_store_dwordx4 v[52:53], v[48:51], off nt
	v_mul_f32_e32 v46, v46, v46
	v_mul_f32_e32 v47, v47, v47
	v_cvt_pk_bf16_f32 v44, v44, v45
	v_cvt_pk_bf16_f32 v45, v46, v47
	v_cvt_pk_bf16_f32 v40, v40, v41
	v_cvt_pk_bf16_f32 v41, v42, v43
	v_mul_f32_e32 v36, v36, v36
	v_mul_f32_e32 v37, v37, v37
	v_mul_f32_e32 v34, v34, v34
	v_mul_f32_e32 v35, v35, v35
	v_cvt_pk_bf16_f32 v42, v36, v37
	v_cvt_pk_bf16_f32 v38, v38, v39
	v_cvt_pk_bf16_f32 v39, v32, v33
	v_cvt_pk_bf16_f32 v43, v34, v35
	v_add_u32_e32 v32, 0x90, v146
	v_cndmask_b32_e64 v33, v41, v43, s[0:1]
	v_cndmask_b32_e64 v34, v45, v38, s[0:1]
	v_cndmask_b32_e64 v35, v40, v39, s[0:1]
	v_mov_b32_dpp v49, v33 quad_perm:[1,0,3,2] row_mask:0xf bank_mask:0xf bound_ctrl:1
	v_ashrrev_i32_e32 v33, 31, v32
	v_lshlrev_b64 v[32:33], 13, v[32:33]
	v_cndmask_b32_e64 v36, v44, v42, s[0:1]
	v_lshl_add_u64 v[32:33], s[60:61], 0, v[32:33]
	v_mov_b32_dpp v47, v34 quad_perm:[1,0,3,2] row_mask:0xf bank_mask:0xf bound_ctrl:1
	v_mov_b32_dpp v46, v36 quad_perm:[1,0,3,2] row_mask:0xf bank_mask:0xf bound_ctrl:1
	v_mov_b32_dpp v48, v35 quad_perm:[1,0,3,2] row_mask:0xf bank_mask:0xf bound_ctrl:1
	v_lshl_add_u64 v[32:33], v[32:33], 0, v[112:113]
	v_lshl_add_u64 v[36:37], v[32:33], 0, v[136:137]
	v_cndmask_b32_e64 v33, v47, v45, s[0:1]
	v_cndmask_b32_e64 v35, v49, v41, s[0:1]
	v_cndmask_b32_e64 v32, v46, v44, s[0:1]
	v_cndmask_b32_e64 v34, v48, v40, s[0:1]
	global_store_dwordx4 v[36:37], v[32:35], off nt
	v_add_co_u32_e32 v36, vcc, s43, v36
	s_nop 0
	v_cndmask_b32_e64 v33, v38, v47, s[0:1]
	ds_read_b32 v38, v155 offset:640
	v_cndmask_b32_e64 v35, v43, v49, s[0:1]
	v_cndmask_b32_e64 v32, v42, v46, s[0:1]
	v_cndmask_b32_e64 v34, v39, v48, s[0:1]
	v_addc_co_u32_e32 v37, vcc, 0, v37, vcc
	s_waitcnt lgkmcnt(0)
	v_pk_mul_f32 v[28:29], v[28:29], v[38:39] op_sel_hi:[1,0]
	v_pk_mul_f32 v[26:27], v[26:27], v[38:39] op_sel_hi:[1,0]
	v_pk_mul_f32 v[24:25], v[24:25], v[38:39] op_sel_hi:[1,0]
	v_pk_mul_f32 v[22:23], v[22:23], v[38:39] op_sel_hi:[1,0]
	v_pk_mul_f32 v[16:17], v[16:17], v[38:39] op_sel_hi:[1,0]
	v_pk_mul_f32 v[30:31], v[30:31], v[38:39] op_sel_hi:[1,0]
	v_max_f32_e32 v28, 0, v28
	v_max_f32_e32 v24, 0, v24
	v_max_f32_e32 v29, 0, v29
	v_max_f32_e32 v25, 0, v25
	v_max_f32_e32 v26, 0, v26
	v_max_f32_e32 v27, 0, v27
	v_pk_mul_f32 v[20:21], v[20:21], v[38:39] op_sel_hi:[1,0]
	v_pk_mul_f32 v[18:19], v[18:19], v[38:39] op_sel_hi:[1,0]
	v_max_f32_e32 v16, 0, v16
	v_max_f32_e32 v17, 0, v17
	v_max_f32_e32 v22, 0, v22
	v_max_f32_e32 v23, 0, v23
	v_mul_f32_e32 v28, v28, v28
	v_mul_f32_e32 v24, v24, v24
	v_mul_f32_e32 v29, v29, v29
	v_mul_f32_e32 v25, v25, v25
	v_max_f32_e32 v30, 0, v30
	v_mul_f32_e32 v26, v26, v26
	v_max_f32_e32 v31, 0, v31
	v_mul_f32_e32 v27, v27, v27
	v_max_f32_e32 v20, 0, v20
	v_mul_f32_e32 v16, v16, v16
	v_max_f32_e32 v21, 0, v21
	v_mul_f32_e32 v17, v17, v17
	v_max_f32_e32 v18, 0, v18
	v_mul_f32_e32 v22, v22, v22
	v_max_f32_e32 v19, 0, v19
	v_mul_f32_e32 v23, v23, v23
	global_store_dwordx4 v[36:37], v[32:35], off nt
	v_mul_f32_e32 v30, v30, v30
	v_mul_f32_e32 v31, v31, v31
	v_cvt_pk_bf16_f32 v28, v28, v29
	v_cvt_pk_bf16_f32 v29, v30, v31
	v_cvt_pk_bf16_f32 v24, v24, v25
	v_cvt_pk_bf16_f32 v25, v26, v27
	v_mul_f32_e32 v20, v20, v20
	v_mul_f32_e32 v21, v21, v21
	v_mul_f32_e32 v18, v18, v18
	v_mul_f32_e32 v19, v19, v19
	v_cvt_pk_bf16_f32 v26, v20, v21
	v_cvt_pk_bf16_f32 v22, v22, v23
	v_cvt_pk_bf16_f32 v23, v16, v17
	v_cvt_pk_bf16_f32 v27, v18, v19
	v_add_u32_e32 v16, 0xa0, v146
	v_cndmask_b32_e64 v17, v25, v27, s[0:1]
	v_cndmask_b32_e64 v18, v29, v22, s[0:1]
	v_cndmask_b32_e64 v19, v24, v23, s[0:1]
	v_mov_b32_dpp v33, v17 quad_perm:[1,0,3,2] row_mask:0xf bank_mask:0xf bound_ctrl:1
	v_ashrrev_i32_e32 v17, 31, v16
	v_lshlrev_b64 v[16:17], 13, v[16:17]
	v_cndmask_b32_e64 v20, v28, v26, s[0:1]
	v_lshl_add_u64 v[16:17], s[60:61], 0, v[16:17]
	v_mov_b32_dpp v31, v18 quad_perm:[1,0,3,2] row_mask:0xf bank_mask:0xf bound_ctrl:1
	v_mov_b32_dpp v30, v20 quad_perm:[1,0,3,2] row_mask:0xf bank_mask:0xf bound_ctrl:1
	v_mov_b32_dpp v32, v19 quad_perm:[1,0,3,2] row_mask:0xf bank_mask:0xf bound_ctrl:1
	v_lshl_add_u64 v[16:17], v[16:17], 0, v[112:113]
	v_lshl_add_u64 v[20:21], v[16:17], 0, v[136:137]
	v_cndmask_b32_e64 v17, v31, v29, s[0:1]
	v_cndmask_b32_e64 v19, v33, v25, s[0:1]
	v_cndmask_b32_e64 v16, v30, v28, s[0:1]
	v_cndmask_b32_e64 v18, v32, v24, s[0:1]
	global_store_dwordx4 v[20:21], v[16:19], off nt
	v_add_co_u32_e32 v20, vcc, s43, v20
	s_nop 0
	v_cndmask_b32_e64 v17, v22, v31, s[0:1]
	ds_read_b32 v22, v155 offset:704
	v_cndmask_b32_e64 v19, v27, v33, s[0:1]
	v_cndmask_b32_e64 v16, v26, v30, s[0:1]
	v_cndmask_b32_e64 v18, v23, v32, s[0:1]
	v_addc_co_u32_e32 v21, vcc, 0, v21, vcc
	s_waitcnt lgkmcnt(0)
	v_pk_mul_f32 v[12:13], v[12:13], v[22:23] op_sel_hi:[1,0]
	v_pk_mul_f32 v[10:11], v[10:11], v[22:23] op_sel_hi:[1,0]
	v_pk_mul_f32 v[8:9], v[8:9], v[22:23] op_sel_hi:[1,0]
	v_pk_mul_f32 v[6:7], v[6:7], v[22:23] op_sel_hi:[1,0]
	v_pk_mul_f32 v[0:1], v[0:1], v[22:23] op_sel_hi:[1,0]
	v_pk_mul_f32 v[14:15], v[14:15], v[22:23] op_sel_hi:[1,0]
	v_max_f32_e32 v12, 0, v12
	v_max_f32_e32 v8, 0, v8
	v_max_f32_e32 v13, 0, v13
	v_max_f32_e32 v9, 0, v9
	v_max_f32_e32 v10, 0, v10
	v_max_f32_e32 v11, 0, v11
	v_pk_mul_f32 v[4:5], v[4:5], v[22:23] op_sel_hi:[1,0]
	v_pk_mul_f32 v[2:3], v[2:3], v[22:23] op_sel_hi:[1,0]
	v_max_f32_e32 v0, 0, v0
	v_max_f32_e32 v1, 0, v1
	v_max_f32_e32 v6, 0, v6
	v_max_f32_e32 v7, 0, v7
	v_mul_f32_e32 v12, v12, v12
	v_mul_f32_e32 v8, v8, v8
	v_mul_f32_e32 v13, v13, v13
	v_mul_f32_e32 v9, v9, v9
	v_max_f32_e32 v14, 0, v14
	v_mul_f32_e32 v10, v10, v10
	v_max_f32_e32 v15, 0, v15
	v_mul_f32_e32 v11, v11, v11
	v_max_f32_e32 v4, 0, v4
	v_mul_f32_e32 v0, v0, v0
	v_max_f32_e32 v5, 0, v5
	v_mul_f32_e32 v1, v1, v1
	v_max_f32_e32 v2, 0, v2
	v_mul_f32_e32 v6, v6, v6
	v_max_f32_e32 v3, 0, v3
	v_mul_f32_e32 v7, v7, v7
	global_store_dwordx4 v[20:21], v[16:19], off nt
	v_mul_f32_e32 v14, v14, v14
	v_mul_f32_e32 v15, v15, v15
	v_cvt_pk_bf16_f32 v12, v12, v13
	v_cvt_pk_bf16_f32 v13, v14, v15
	v_cvt_pk_bf16_f32 v8, v8, v9
	v_cvt_pk_bf16_f32 v9, v10, v11
	v_mul_f32_e32 v4, v4, v4
	v_mul_f32_e32 v5, v5, v5
	v_mul_f32_e32 v2, v2, v2
	v_mul_f32_e32 v3, v3, v3
	v_cvt_pk_bf16_f32 v10, v4, v5
	v_cvt_pk_bf16_f32 v6, v6, v7
	v_cvt_pk_bf16_f32 v7, v0, v1
	v_cvt_pk_bf16_f32 v11, v2, v3
	v_add_u32_e32 v0, 0xb0, v146
	v_cndmask_b32_e64 v1, v9, v11, s[0:1]
	v_cndmask_b32_e64 v2, v13, v6, s[0:1]
	v_cndmask_b32_e64 v3, v8, v7, s[0:1]
	v_mov_b32_dpp v17, v1 quad_perm:[1,0,3,2] row_mask:0xf bank_mask:0xf bound_ctrl:1
	v_ashrrev_i32_e32 v1, 31, v0
	v_lshlrev_b64 v[0:1], 13, v[0:1]
	v_cndmask_b32_e64 v4, v12, v10, s[0:1]
	v_lshl_add_u64 v[0:1], s[60:61], 0, v[0:1]
	v_mov_b32_dpp v15, v2 quad_perm:[1,0,3,2] row_mask:0xf bank_mask:0xf bound_ctrl:1
	v_mov_b32_dpp v14, v4 quad_perm:[1,0,3,2] row_mask:0xf bank_mask:0xf bound_ctrl:1
	v_mov_b32_dpp v16, v3 quad_perm:[1,0,3,2] row_mask:0xf bank_mask:0xf bound_ctrl:1
	v_lshl_add_u64 v[0:1], v[0:1], 0, v[112:113]
	v_lshl_add_u64 v[4:5], v[0:1], 0, v[136:137]
	v_cndmask_b32_e64 v1, v15, v13, s[0:1]
	v_cndmask_b32_e64 v3, v17, v9, s[0:1]
	v_cndmask_b32_e64 v0, v14, v12, s[0:1]
	v_cndmask_b32_e64 v2, v16, v8, s[0:1]
	global_store_dwordx4 v[4:5], v[0:3], off nt
	v_add_co_u32_e32 v4, vcc, 0x2000, v4
	s_nop 0
	v_cndmask_b32_e64 v1, v6, v15, s[0:1]
	v_addc_co_u32_e32 v5, vcc, 0, v5, vcc
	v_cndmask_b32_e64 v3, v11, v17, s[0:1]
	v_cndmask_b32_e64 v0, v10, v14, s[0:1]
	v_cndmask_b32_e64 v2, v7, v16, s[0:1]
	s_andn2_b64 vcc, exec, s[6:7]
	s_mov_b64 s[6:7], -1
	global_store_dwordx4 v[4:5], v[0:3], off nt
	s_cbranch_vccnz .LBB0_743
	s_andn2_b64 vcc, exec, s[10:11]
	s_cbranch_vccnz .LBB0_742
	s_mov_b32 s98, 1
	s_branch .LBB0_742

.LBB0_818:
	s_lshl_b32 s5, s5, 5
	s_mov_b64 s[8:9], 0x80
	s_and_b32 s5, s5, 0x60
	s_add_i32 m0, s2, 0x18000
	v_lshl_add_u64 v[6:7], v[6:7], 0, s[8:9]
	s_lshl_b32 s16, s1, 13
	s_lshl_b32 s17, s5, 7
	s_waitcnt vmcnt(2)
	s_barrier
	global_load_lds_dwordx4 v[6:7], off
	v_lshl_add_u64 v[4:5], v[4:5], 0, s[8:9]
	s_add_i32 m0, s2, 0x1a000
	s_add_i32 s44, s2, 0x8000
	s_add_i32 s45, s2, 0xa000
	global_load_lds_dwordx4 v[4:5], off
	v_lshl_add_u64 v[0:1], v[0:1], 0, s[8:9]
	s_mov_b32 m0, s44
	s_add_u32 s10, s40, 0x100080
	global_load_lds_dwordx4 v[0:1], off
	v_lshl_add_u64 v[0:1], v[2:3], 0, s[8:9]
	s_mov_b32 m0, s45
	s_addc_u32 s11, s41, 0
	global_load_lds_dwordx4 v[0:1], off
	s_add_i32 m0, s2, 0x1c000
	v_lshl_add_u64 v[0:1], s[10:11], 0, v[128:129]
	global_load_lds_dwordx4 v[0:1], off
	v_lshl_add_u64 v[0:1], s[10:11], 0, v[130:131]
	s_add_i32 m0, s2, 0x1e000
	s_cmpk_lt_u32 s4, 0x100
	global_load_lds_dwordx4 v[0:1], off
	v_bfe_u32 v1, v215, 4, 2
	v_and_b32_e32 v0, 15, v215
	v_lshlrev_b32_e32 v2, 4, v1
	v_lshl_or_b32 v133, s1, 6, v0
	v_lshl_or_b32 v0, v0, 6, v2
	v_lshlrev_b32_e32 v2, 2, v215
	v_and_b32_e32 v2, 32, v2
	v_bitop3_b32 v3, v0, s16, v2 bitop3:0xde
	v_bitop3_b32 v192, v0, s17, v2 bitop3:0xde
	v_lshlrev_b32_e32 v0, 16, v8
	v_and_b32_e32 v0, 0xfffe0000, v0
	v_lshl_or_b32 v194, v1, 2, s5
	v_lshl_add_u32 v0, v9, 13, v0
	v_and_b32_e32 v1, 1, v8
	v_lshl_or_b32 v0, v1, 6, v0
	v_lshl_add_u32 v134, v10, 1, v0
	v_lshlrev_b32_e32 v0, 16, v11
	v_and_b32_e32 v0, 0xfffe0000, v0
	s_waitcnt vmcnt(6)
	v_lshl_add_u32 v0, v12, 13, v0
	v_and_b32_e32 v1, 1, v11
	s_cselect_b64 s[10:11], -1, 0
	v_and_b32_e32 v193, 1, v215
	v_lshl_or_b32 v0, v1, 6, v0
	s_add_i32 s46, 0, 0x10000
	s_add_i32 s47, 0, 0x14000
	s_sext_i32_i8 s53, s0
	v_cmp_eq_u32_e64 s[0:1], 0, v193
	v_lshlrev_b32_e32 v132, 4, v193
	v_mov_b32_e32 v135, v129
	v_lshl_add_u32 v136, v13, 1, v0
	v_mov_b32_e32 v137, v129
	v_mov_b64_e32 v[138:139], 0x200
	v_mov_b64_e32 v[140:141], 0x1ff
	v_add_u32_e32 v195, s46, v192
	v_add_u32_e32 v196, s47, v192
	v_add_u32_e32 v197, 0, v3
	s_mov_b64 s[16:17], 0x40000
	s_mov_b32 s48, 0x40000
	s_mov_b64 s[18:19], 0x48000
	s_mov_b32 s49, 0x48000
	s_mov_b64 s[20:21], 0x50000
	s_mov_b32 s50, 0x50000
	s_mov_b64 s[22:23], 0x58000
	s_mov_b32 s51, 0x58000
	s_movk_i32 s52, 0x1000
	s_barrier
	s_mov_b32 s98, 0
	s_branch .LBB0_821

.LBB0_827:
	s_ashr_i32 s27, s26, 31
	s_lshl_b64 s[28:29], s[26:27], 21
	s_add_u32 s28, s60, s28
	s_addc_u32 s29, s61, s29
	s_and_b64 s[30:31], s[4:5], exec
	s_cselect_b32 s27, s29, s39
	s_cselect_b32 s54, s28, s38
	s_ashr_i32 s25, s24, 31
	s_lshl_b64 s[30:31], s[24:25], 21
	s_add_u32 s30, s12, s30
	s_addc_u32 s31, s13, s31
	s_and_b64 s[42:43], s[4:5], exec
	s_cselect_b32 s25, s31, s41
	s_cselect_b32 s55, s30, s40
	s_add_u32 s38, s38, 0x100080
	s_addc_u32 s39, s39, 0
	s_add_u32 s56, s40, 0x100
	s_addc_u32 s57, s41, 0
	s_mov_b32 s58, -2
	s_cmp_eq_u32 s98, 0
	s_cbranch_scc1 .Ltb_skip_3
	s_barrier
	s_mov_b32 s98, 0
.Ltb_skip_3:
	ds_read_b128 v[142:145], v195
	ds_read_b128 v[146:149], v195 offset:1024
	ds_read_b128 v[150:153], v195 offset:2048
	ds_read_b128 v[154:157], v195 offset:3072
	ds_read_b128 v[158:161], v196
	ds_read_b128 v[162:165], v196 offset:1024
	ds_read_b128 v[166:169], v196 offset:2048
	ds_read_b128 v[170:173], v196 offset:3072
	s_add_u32 s40, s38, 0xfff00080
	s_addc_u32 s41, s39, -1
	s_cmp_eq_u32 s58, 60
	s_cselect_b32 s43, s27, s41
	s_cselect_b32 s42, s54, s40
	s_cselect_b32 s41, s25, s57
	s_cselect_b32 s40, s55, s56
	v_lshl_add_u64 v[190:191], s[38:39], 0, v[134:135]
	s_add_i32 m0, s2, 0xc000
	ds_read_b128 v[174:177], v197
	ds_read_b128 v[178:181], v197 offset:1024
	ds_read_b128 v[182:185], v197 offset:2048
	ds_read_b128 v[186:189], v197 offset:3072
	ds_read_b128 v[198:201], v197 offset:4096
	ds_read_b128 v[202:205], v197 offset:5120
	ds_read_b128 v[206:209], v197 offset:6144
	ds_read_b128 v[210:213], v197 offset:7168
	global_load_lds_dwordx4 v[190:191], off
	v_lshl_add_u64 v[190:191], s[38:39], 0, v[136:137]
	s_add_i32 m0, s2, 0xe000
	s_nop 0
	global_load_lds_dwordx4 v[190:191], off
	s_waitcnt vmcnt(8)
	s_waitcnt lgkmcnt(0)
	s_barrier
	s_setprio 1
	s_waitcnt lgkmcnt(0)
	v_mfma_f32_16x16x32_bf16 v[124:127], v[142:145], v[174:177], 0
	v_mfma_f32_16x16x32_bf16 v[124:127], v[146:149], v[178:181], v[124:127]
	v_mfma_f32_16x16x32_bf16 v[120:123], v[150:153], v[174:177], 0
	v_mfma_f32_16x16x32_bf16 v[120:123], v[154:157], v[178:181], v[120:123]
	v_mfma_f32_16x16x32_bf16 v[104:107], v[150:153], v[182:185], 0
	v_mfma_f32_16x16x32_bf16 v[104:107], v[154:157], v[186:189], v[104:107]
	v_mfma_f32_16x16x32_bf16 v[108:111], v[142:145], v[182:185], 0
	v_mfma_f32_16x16x32_bf16 v[108:111], v[146:149], v[186:189], v[108:111]
	v_mfma_f32_16x16x32_bf16 v[92:95], v[142:145], v[198:201], 0
	v_mfma_f32_16x16x32_bf16 v[92:95], v[146:149], v[202:205], v[92:95]
	v_mfma_f32_16x16x32_bf16 v[88:91], v[150:153], v[198:201], 0
	v_mfma_f32_16x16x32_bf16 v[88:91], v[154:157], v[202:205], v[88:91]
	v_mfma_f32_16x16x32_bf16 v[72:75], v[150:153], v[206:209], 0
	v_mfma_f32_16x16x32_bf16 v[72:75], v[154:157], v[210:213], v[72:75]
	v_mfma_f32_16x16x32_bf16 v[76:79], v[142:145], v[206:209], 0
	v_mfma_f32_16x16x32_bf16 v[76:79], v[146:149], v[210:213], v[76:79]
	s_setprio 0
	s_setprio 1
	v_mfma_f32_16x16x32_bf16 v[116:119], v[158:161], v[174:177], 0
	v_mfma_f32_16x16x32_bf16 v[116:119], v[162:165], v[178:181], v[116:119]
	v_mfma_f32_16x16x32_bf16 v[112:115], v[166:169], v[174:177], 0
	v_mfma_f32_16x16x32_bf16 v[112:115], v[170:173], v[178:181], v[112:115]
	v_mfma_f32_16x16x32_bf16 v[96:99], v[166:169], v[182:185], 0
	v_mfma_f32_16x16x32_bf16 v[96:99], v[170:173], v[186:189], v[96:99]
	v_mfma_f32_16x16x32_bf16 v[100:103], v[158:161], v[182:185], 0
	v_mfma_f32_16x16x32_bf16 v[100:103], v[162:165], v[186:189], v[100:103]
	v_mfma_f32_16x16x32_bf16 v[84:87], v[158:161], v[198:201], 0
	v_mfma_f32_16x16x32_bf16 v[84:87], v[162:165], v[202:205], v[84:87]
	v_mfma_f32_16x16x32_bf16 v[80:83], v[166:169], v[198:201], 0
	v_mfma_f32_16x16x32_bf16 v[80:83], v[170:173], v[202:205], v[80:83]
	v_mfma_f32_16x16x32_bf16 v[64:67], v[166:169], v[206:209], 0
	v_mfma_f32_16x16x32_bf16 v[64:67], v[170:173], v[210:213], v[64:67]
	v_mfma_f32_16x16x32_bf16 v[68:71], v[158:161], v[206:209], 0
	v_mfma_f32_16x16x32_bf16 v[68:71], v[162:165], v[210:213], v[68:71]
	s_setprio 0
	s_barrier
	s_add_i32 s59, s46, s3
	v_lshl_add_u64 v[190:191], s[40:41], 0, v[128:129]
	s_mov_b32 m0, s59
	ds_read_b128 v[174:177], v197 offset:16384
	ds_read_b128 v[178:181], v197 offset:17408
	ds_read_b128 v[182:185], v197 offset:18432
	ds_read_b128 v[186:189], v197 offset:19456
	ds_read_b128 v[198:201], v197 offset:20480
	ds_read_b128 v[202:205], v197 offset:21504
	ds_read_b128 v[206:209], v197 offset:22528
	ds_read_b128 v[210:213], v197 offset:23552
	global_load_lds_dwordx4 v[190:191], off
	s_add_i32 m0, s59, 0x2000
	s_add_u32 s62, s40, 0x100000
	v_lshl_add_u64 v[214:215], s[40:41], 0, v[130:131]
	s_addc_u32 s63, s41, 0
	s_add_i32 s59, s47, s3
	global_load_lds_dwordx4 v[214:215], off
	v_lshl_add_u64 v[216:217], s[62:63], 0, v[128:129]
	s_mov_b32 m0, s59
	v_lshl_add_u64 v[218:219], s[42:43], 0, v[130:131]
	global_load_lds_dwordx4 v[216:217], off
	v_lshl_add_u64 v[216:217], s[62:63], 0, v[130:131]
	s_add_i32 m0, s59, 0x2000
	s_nop 0
	global_load_lds_dwordx4 v[216:217], off
	v_lshl_add_u64 v[216:217], s[42:43], 0, v[128:129]
	s_mov_b32 m0, s2
	s_nop 0
	global_load_lds_dwordx4 v[216:217], off
	s_mov_b32 m0, s33
	s_nop 0
	global_load_lds_dwordx4 v[218:219], off
	s_waitcnt vmcnt(8)
	s_waitcnt lgkmcnt(0)
	s_barrier
	s_setprio 1
	s_waitcnt lgkmcnt(0)
	v_mfma_f32_16x16x32_bf16 v[60:63], v[142:145], v[174:177], 0
	v_mfma_f32_16x16x32_bf16 v[60:63], v[146:149], v[178:181], v[60:63]
	v_mfma_f32_16x16x32_bf16 v[56:59], v[150:153], v[174:177], 0
	v_mfma_f32_16x16x32_bf16 v[56:59], v[154:157], v[178:181], v[56:59]
	v_mfma_f32_16x16x32_bf16 v[40:43], v[150:153], v[182:185], 0
	v_mfma_f32_16x16x32_bf16 v[40:43], v[154:157], v[186:189], v[40:43]
	v_mfma_f32_16x16x32_bf16 v[44:47], v[142:145], v[182:185], 0
	v_mfma_f32_16x16x32_bf16 v[44:47], v[146:149], v[186:189], v[44:47]
	v_mfma_f32_16x16x32_bf16 v[28:31], v[142:145], v[198:201], 0
	v_mfma_f32_16x16x32_bf16 v[28:31], v[146:149], v[202:205], v[28:31]
	v_mfma_f32_16x16x32_bf16 v[24:27], v[150:153], v[198:201], 0
	v_mfma_f32_16x16x32_bf16 v[24:27], v[154:157], v[202:205], v[24:27]
	v_mfma_f32_16x16x32_bf16 v[8:11], v[150:153], v[206:209], 0
	v_mfma_f32_16x16x32_bf16 v[8:11], v[154:157], v[210:213], v[8:11]
	v_mfma_f32_16x16x32_bf16 v[12:15], v[142:145], v[206:209], 0
	v_mfma_f32_16x16x32_bf16 v[12:15], v[146:149], v[210:213], v[12:15]
	s_setprio 0
	s_setprio 1
	v_mfma_f32_16x16x32_bf16 v[52:55], v[158:161], v[174:177], 0
	v_mfma_f32_16x16x32_bf16 v[52:55], v[162:165], v[178:181], v[52:55]
	v_mfma_f32_16x16x32_bf16 v[48:51], v[166:169], v[174:177], 0
	v_mfma_f32_16x16x32_bf16 v[48:51], v[170:173], v[178:181], v[48:51]
	v_mfma_f32_16x16x32_bf16 v[32:35], v[166:169], v[182:185], 0
	v_mfma_f32_16x16x32_bf16 v[32:35], v[170:173], v[186:189], v[32:35]
	v_mfma_f32_16x16x32_bf16 v[36:39], v[158:161], v[182:185], 0
	v_mfma_f32_16x16x32_bf16 v[36:39], v[162:165], v[186:189], v[36:39]
	v_mfma_f32_16x16x32_bf16 v[20:23], v[158:161], v[198:201], 0
	v_mfma_f32_16x16x32_bf16 v[20:23], v[162:165], v[202:205], v[20:23]
	v_mfma_f32_16x16x32_bf16 v[16:19], v[166:169], v[198:201], 0
	v_mfma_f32_16x16x32_bf16 v[16:19], v[170:173], v[202:205], v[16:19]
	v_mfma_f32_16x16x32_bf16 v[0:3], v[166:169], v[206:209], 0
	v_mfma_f32_16x16x32_bf16 v[0:3], v[170:173], v[210:213], v[0:3]
	v_mfma_f32_16x16x32_bf16 v[4:7], v[158:161], v[206:209], 0
	v_mfma_f32_16x16x32_bf16 v[4:7], v[162:165], v[210:213], v[4:7]
	s_setprio 0
	s_barrier
	s_add_i32 s59, 0, 0x18000
	s_add_i32 s62, 0, 0x1c000
	v_add_u32_e32 v154, s59, v192
	v_add_u32_e32 v170, s62, v192
	ds_read_b128 v[142:145], v154
	ds_read_b128 v[146:149], v154 offset:1024
	ds_read_b128 v[150:153], v154 offset:2048
	ds_read_b128 v[154:157], v154 offset:3072
	ds_read_b128 v[158:161], v170
	ds_read_b128 v[162:165], v170 offset:1024
	ds_read_b128 v[166:169], v170 offset:2048
	ds_read_b128 v[170:173], v170 offset:3072
	s_add_u32 s42, s42, 0x100000
	s_addc_u32 s43, s43, 0
	s_mov_b32 m0, s34
	v_lshl_add_u64 v[220:221], s[42:43], 0, v[128:129]
	ds_read_b128 v[174:177], v197 offset:32768
	ds_read_b128 v[178:181], v197 offset:33792
	ds_read_b128 v[182:185], v197 offset:34816
	ds_read_b128 v[186:189], v197 offset:35840
	ds_read_b128 v[198:201], v197 offset:36864
	ds_read_b128 v[202:205], v197 offset:37888
	ds_read_b128 v[206:209], v197 offset:38912
	ds_read_b128 v[210:213], v197 offset:39936
	global_load_lds_dwordx4 v[220:221], off
	v_lshl_add_u64 v[220:221], s[42:43], 0, v[130:131]
	s_mov_b32 m0, s35
	s_nop 0
	global_load_lds_dwordx4 v[220:221], off
	s_waitcnt vmcnt(8)
	s_waitcnt lgkmcnt(0)
	s_barrier
	s_setprio 1
	s_waitcnt lgkmcnt(0)
	v_mfma_f32_16x16x32_bf16 v[124:127], v[142:145], v[174:177], v[124:127]
	v_mfma_f32_16x16x32_bf16 v[124:127], v[146:149], v[178:181], v[124:127]
	v_mfma_f32_16x16x32_bf16 v[120:123], v[150:153], v[174:177], v[120:123]
	v_mfma_f32_16x16x32_bf16 v[120:123], v[154:157], v[178:181], v[120:123]
	v_mfma_f32_16x16x32_bf16 v[104:107], v[150:153], v[182:185], v[104:107]
	v_mfma_f32_16x16x32_bf16 v[104:107], v[154:157], v[186:189], v[104:107]
	v_mfma_f32_16x16x32_bf16 v[108:111], v[142:145], v[182:185], v[108:111]
	v_mfma_f32_16x16x32_bf16 v[108:111], v[146:149], v[186:189], v[108:111]
	v_mfma_f32_16x16x32_bf16 v[92:95], v[142:145], v[198:201], v[92:95]
	v_mfma_f32_16x16x32_bf16 v[92:95], v[146:149], v[202:205], v[92:95]
	v_mfma_f32_16x16x32_bf16 v[88:91], v[150:153], v[198:201], v[88:91]
	v_mfma_f32_16x16x32_bf16 v[88:91], v[154:157], v[202:205], v[88:91]
	v_mfma_f32_16x16x32_bf16 v[72:75], v[150:153], v[206:209], v[72:75]
	v_mfma_f32_16x16x32_bf16 v[72:75], v[154:157], v[210:213], v[72:75]
	v_mfma_f32_16x16x32_bf16 v[76:79], v[142:145], v[206:209], v[76:79]
	v_mfma_f32_16x16x32_bf16 v[76:79], v[146:149], v[210:213], v[76:79]
	s_setprio 0
	s_setprio 1
	v_mfma_f32_16x16x32_bf16 v[116:119], v[158:161], v[174:177], v[116:119]
	v_mfma_f32_16x16x32_bf16 v[116:119], v[162:165], v[178:181], v[116:119]
	v_mfma_f32_16x16x32_bf16 v[112:115], v[166:169], v[174:177], v[112:115]
	v_mfma_f32_16x16x32_bf16 v[112:115], v[170:173], v[178:181], v[112:115]
	v_mfma_f32_16x16x32_bf16 v[96:99], v[166:169], v[182:185], v[96:99]
	v_mfma_f32_16x16x32_bf16 v[96:99], v[170:173], v[186:189], v[96:99]
	v_mfma_f32_16x16x32_bf16 v[100:103], v[158:161], v[182:185], v[100:103]
	v_mfma_f32_16x16x32_bf16 v[100:103], v[162:165], v[186:189], v[100:103]
	v_mfma_f32_16x16x32_bf16 v[84:87], v[158:161], v[198:201], v[84:87]
	v_mfma_f32_16x16x32_bf16 v[84:87], v[162:165], v[202:205], v[84:87]
	v_mfma_f32_16x16x32_bf16 v[80:83], v[166:169], v[198:201], v[80:83]
	v_mfma_f32_16x16x32_bf16 v[80:83], v[170:173], v[202:205], v[80:83]
	v_mfma_f32_16x16x32_bf16 v[64:67], v[166:169], v[206:209], v[64:67]
	v_mfma_f32_16x16x32_bf16 v[64:67], v[170:173], v[210:213], v[64:67]
	v_mfma_f32_16x16x32_bf16 v[68:71], v[158:161], v[206:209], v[68:71]
	v_mfma_f32_16x16x32_bf16 v[68:71], v[162:165], v[210:213], v[68:71]
	s_setprio 0
	s_barrier
	s_add_i32 s42, s59, s3
	v_lshl_add_u64 v[190:191], v[190:191], 0, s[8:9]
	s_mov_b32 m0, s42
	ds_read_b128 v[174:177], v197 offset:49152
	ds_read_b128 v[178:181], v197 offset:50176
	ds_read_b128 v[182:185], v197 offset:51200
	ds_read_b128 v[186:189], v197 offset:52224
	ds_read_b128 v[198:201], v197 offset:53248
	ds_read_b128 v[202:205], v197 offset:54272
	ds_read_b128 v[206:209], v197 offset:55296
	ds_read_b128 v[210:213], v197 offset:56320
	global_load_lds_dwordx4 v[190:191], off
	s_add_i32 m0, s42, 0x2000
	s_add_u32 s40, s40, 0x100080
	v_lshl_add_u64 v[190:191], v[214:215], 0, s[8:9]
	s_addc_u32 s41, s41, 0
	s_add_i32 s42, s62, s3
	global_load_lds_dwordx4 v[190:191], off
	v_lshl_add_u64 v[190:191], s[40:41], 0, v[128:129]
	s_mov_b32 m0, s42
	s_nop 0
	global_load_lds_dwordx4 v[190:191], off
	v_lshl_add_u64 v[190:191], s[40:41], 0, v[130:131]
	s_add_i32 m0, s42, 0x2000
	s_nop 0
	global_load_lds_dwordx4 v[190:191], off
	v_lshl_add_u64 v[190:191], v[216:217], 0, s[8:9]
	s_mov_b32 m0, s44
	s_nop 0
	global_load_lds_dwordx4 v[190:191], off
	v_lshl_add_u64 v[190:191], v[218:219], 0, s[8:9]
	s_mov_b32 m0, s45
	s_nop 0
	global_load_lds_dwordx4 v[190:191], off
	s_waitcnt vmcnt(8)
	s_waitcnt lgkmcnt(0)
	s_barrier
	s_setprio 1
	s_waitcnt lgkmcnt(0)
	v_mfma_f32_16x16x32_bf16 v[60:63], v[142:145], v[174:177], v[60:63]
	v_mfma_f32_16x16x32_bf16 v[60:63], v[146:149], v[178:181], v[60:63]
	v_mfma_f32_16x16x32_bf16 v[56:59], v[150:153], v[174:177], v[56:59]
	v_mfma_f32_16x16x32_bf16 v[56:59], v[154:157], v[178:181], v[56:59]
	v_mfma_f32_16x16x32_bf16 v[40:43], v[150:153], v[182:185], v[40:43]
	v_mfma_f32_16x16x32_bf16 v[40:43], v[154:157], v[186:189], v[40:43]
	v_mfma_f32_16x16x32_bf16 v[44:47], v[142:145], v[182:185], v[44:47]
	v_mfma_f32_16x16x32_bf16 v[44:47], v[146:149], v[186:189], v[44:47]
	v_mfma_f32_16x16x32_bf16 v[28:31], v[142:145], v[198:201], v[28:31]
	v_mfma_f32_16x16x32_bf16 v[28:31], v[146:149], v[202:205], v[28:31]
	v_mfma_f32_16x16x32_bf16 v[24:27], v[150:153], v[198:201], v[24:27]
	v_mfma_f32_16x16x32_bf16 v[24:27], v[154:157], v[202:205], v[24:27]
	v_mfma_f32_16x16x32_bf16 v[8:11], v[150:153], v[206:209], v[8:11]
	v_mfma_f32_16x16x32_bf16 v[8:11], v[154:157], v[210:213], v[8:11]
	v_mfma_f32_16x16x32_bf16 v[12:15], v[142:145], v[206:209], v[12:15]
	v_mfma_f32_16x16x32_bf16 v[12:15], v[146:149], v[210:213], v[12:15]
	s_setprio 0
	s_setprio 1
	v_mfma_f32_16x16x32_bf16 v[52:55], v[158:161], v[174:177], v[52:55]
	v_mfma_f32_16x16x32_bf16 v[52:55], v[162:165], v[178:181], v[52:55]
	v_mfma_f32_16x16x32_bf16 v[48:51], v[166:169], v[174:177], v[48:51]
	v_mfma_f32_16x16x32_bf16 v[48:51], v[170:173], v[178:181], v[48:51]
	v_mfma_f32_16x16x32_bf16 v[32:35], v[166:169], v[182:185], v[32:35]
	v_mfma_f32_16x16x32_bf16 v[32:35], v[170:173], v[186:189], v[32:35]
	v_mfma_f32_16x16x32_bf16 v[36:39], v[158:161], v[182:185], v[36:39]
	v_mfma_f32_16x16x32_bf16 v[36:39], v[162:165], v[186:189], v[36:39]
	v_mfma_f32_16x16x32_bf16 v[20:23], v[158:161], v[198:201], v[20:23]
	v_mfma_f32_16x16x32_bf16 v[20:23], v[162:165], v[202:205], v[20:23]
	v_mfma_f32_16x16x32_bf16 v[16:19], v[166:169], v[198:201], v[16:19]
	v_mfma_f32_16x16x32_bf16 v[16:19], v[170:173], v[202:205], v[16:19]
	v_mfma_f32_16x16x32_bf16 v[0:3], v[166:169], v[206:209], v[0:3]
	v_mfma_f32_16x16x32_bf16 v[0:3], v[170:173], v[210:213], v[0:3]
	v_mfma_f32_16x16x32_bf16 v[4:7], v[158:161], v[206:209], v[4:7]
	v_mfma_f32_16x16x32_bf16 v[4:7], v[162:165], v[210:213], v[4:7]
	s_setprio 0
	s_barrier
	s_add_i32 s58, s58, 2
	s_add_u32 s38, s38, 0x100
	s_addc_u32 s39, s39, 0
	s_add_u32 s56, s56, 0x100
	s_addc_u32 s57, s57, 0

.LBB0_831:
	v_lshl_add_u32 v142, s36, 8, v133
	v_lshl_or_b32 v198, s53, 8, v194
	v_ashrrev_i32_e32 v199, 31, v198
	v_ashrrev_i32_e32 v143, 31, v142
	v_lshl_add_u64 v[144:145], v[198:199], 1, s[14:15]
	v_lshlrev_b64 v[146:147], 11, v[142:143]
	v_lshl_add_u64 v[148:149], v[144:145], 0, v[146:147]
	global_load_dwordx2 v[200:201], v[148:149], off
	global_load_dwordx2 v[202:203], v[148:149], off offset:32
	global_load_dwordx2 v[204:205], v[148:149], off offset:256
	global_load_dwordx2 v[206:207], v[148:149], off offset:288
	v_or_b32_e32 v150, 16, v142
	v_or_b32_e32 v152, 32, v142
	v_or_b32_e32 v154, 48, v142
	v_ashrrev_i32_e32 v151, 31, v150
	v_ashrrev_i32_e32 v153, 31, v152
	v_ashrrev_i32_e32 v155, 31, v154
	v_sub_u32_e32 v146, v142, v193
	v_lshlrev_b64 v[142:143], 11, v[150:151]
	v_lshlrev_b64 v[150:151], 11, v[152:153]
	v_lshlrev_b64 v[152:153], 11, v[154:155]
	v_add_co_u32_e32 v154, vcc, s48, v148
	v_lshl_add_u64 v[142:143], v[144:145], 0, v[142:143]
	s_nop 0
	v_addc_co_u32_e32 v155, vcc, 0, v149, vcc
	v_add_co_u32_e32 v158, vcc, s49, v148
	v_lshl_add_u64 v[150:151], v[144:145], 0, v[150:151]
	s_nop 0
	v_addc_co_u32_e32 v159, vcc, 0, v149, vcc
	v_add_co_u32_e32 v210, vcc, s50, v148
	v_lshl_add_u64 v[144:145], v[144:145], 0, v[152:153]
	s_nop 0
	v_addc_co_u32_e32 v211, vcc, 0, v149, vcc
	v_lshl_add_u64 v[152:153], v[148:149], 0, s[16:17]
	v_lshl_add_u64 v[156:157], v[148:149], 0, s[18:19]
	v_lshl_add_u64 v[208:209], v[148:149], 0, s[20:21]
	v_lshl_add_u64 v[212:213], v[148:149], 0, s[22:23]
	v_add_co_u32_e32 v148, vcc, s51, v148
	v_ashrrev_i32_e32 v147, 31, v146
	s_nop 0
	v_addc_co_u32_e32 v149, vcc, 0, v149, vcc
	global_load_dwordx2 v[214:215], v[142:143], off
	global_load_dwordx2 v[216:217], v[142:143], off offset:32
	global_load_dwordx2 v[218:219], v[142:143], off offset:256
	global_load_dwordx2 v[220:221], v[142:143], off offset:288
	global_load_dwordx2 v[190:191], v[150:151], off
	global_load_dwordx2 v[188:189], v[150:151], off offset:32
	global_load_dwordx2 v[186:187], v[150:151], off offset:256
	global_load_dwordx2 v[184:185], v[150:151], off offset:288
	global_load_dwordx2 v[182:183], v[144:145], off
	global_load_dwordx2 v[180:181], v[144:145], off offset:32
	global_load_dwordx2 v[178:179], v[144:145], off offset:256
	global_load_dwordx2 v[176:177], v[144:145], off offset:288
	global_load_dwordx2 v[174:175], v[154:155], off
	global_load_dwordx2 v[172:173], v[152:153], off offset:32
	global_load_dwordx2 v[170:171], v[152:153], off offset:256
	global_load_dwordx2 v[168:169], v[152:153], off offset:288
	global_load_dwordx2 v[166:167], v[158:159], off
	global_load_dwordx2 v[164:165], v[156:157], off offset:32
	global_load_dwordx2 v[162:163], v[156:157], off offset:256
	global_load_dwordx2 v[160:161], v[156:157], off offset:288
	s_nop 0
	global_load_dwordx2 v[158:159], v[210:211], off
	global_load_dwordx2 v[156:157], v[208:209], off offset:32
	global_load_dwordx2 v[154:155], v[208:209], off offset:256
	global_load_dwordx2 v[152:153], v[208:209], off offset:288
	global_load_dwordx2 v[150:151], v[148:149], off
	s_nop 0
	global_load_dwordx2 v[148:149], v[212:213], off offset:32
	global_load_dwordx2 v[144:145], v[212:213], off offset:256
	global_load_dwordx2 v[142:143], v[212:213], off offset:288
	v_or_b32_e32 v198, v198, v132
	s_waitcnt vmcnt(31)
	v_lshlrev_b32_e32 v208, 16, v200
	v_and_b32_e32 v209, 0xffff0000, v200
	v_lshlrev_b32_e32 v200, 16, v201
	v_and_b32_e32 v201, 0xffff0000, v201
	s_waitcnt vmcnt(30)
	v_lshlrev_b32_e32 v210, 16, v202
	v_and_b32_e32 v211, 0xffff0000, v202
	v_lshlrev_b32_e32 v202, 16, v203
	v_and_b32_e32 v203, 0xffff0000, v203
	v_pk_add_f32 v[208:209], v[124:125], v[208:209]
	v_pk_add_f32 v[124:125], v[126:127], v[200:201]
	v_pk_add_f32 v[200:201], v[122:123], v[202:203]
	v_pk_add_f32 v[126:127], v[120:121], v[210:211]
	v_cndmask_b32_e64 v120, v125, v201, s[0:1]
	v_cndmask_b32_e64 v121, v124, v200, s[0:1]
	v_cndmask_b32_e64 v122, v209, v127, s[0:1]
	v_cndmask_b32_e64 v123, v208, v126, s[0:1]
	v_mov_b32_dpp v212, v121 quad_perm:[1,0,3,2] row_mask:0xf bank_mask:0xf bound_ctrl:1
	v_mov_b32_dpp v213, v120 quad_perm:[1,0,3,2] row_mask:0xf bank_mask:0xf bound_ctrl:1
	v_lshlrev_b64 v[120:121], 12, v[146:147]
	v_mov_b32_dpp v210, v123 quad_perm:[1,0,3,2] row_mask:0xf bank_mask:0xf bound_ctrl:1
	v_mov_b32_dpp v211, v122 quad_perm:[1,0,3,2] row_mask:0xf bank_mask:0xf bound_ctrl:1
	v_lshl_add_u64 v[202:203], s[74:75], 0, v[120:121]
	v_lshlrev_b64 v[120:121], 2, v[198:199]
	v_cndmask_b32_e64 v125, v213, v125, s[0:1]
	v_cndmask_b32_e64 v124, v212, v124, s[0:1]
	v_cndmask_b32_e64 v123, v211, v209, s[0:1]
	v_cndmask_b32_e64 v122, v210, v208, s[0:1]
	v_lshl_add_u64 v[198:199], v[202:203], 0, v[120:121]
	global_store_dwordx4 v[198:199], v[122:125], off nt
	s_nop 1
	v_cndmask_b32_e64 v122, v126, v210, s[0:1]
	v_add_co_u32_e32 v126, vcc, s52, v198
	v_cndmask_b32_e64 v125, v201, v213, s[0:1]
	v_cndmask_b32_e64 v124, v200, v212, s[0:1]
	v_cndmask_b32_e64 v123, v127, v211, s[0:1]
	v_addc_co_u32_e32 v127, vcc, 0, v199, vcc
	global_store_dwordx4 v[126:127], v[122:125], off nt
	s_nop 1
	s_waitcnt vmcnt(31)
	v_lshlrev_b32_e32 v122, 16, v204
	v_and_b32_e32 v123, 0xffff0000, v204
	v_lshlrev_b32_e32 v124, 16, v205
	v_and_b32_e32 v125, 0xffff0000, v205
	v_pk_add_f32 v[116:117], v[116:117], v[122:123]
	v_pk_add_f32 v[118:119], v[118:119], v[124:125]
	s_waitcnt vmcnt(30)
	v_lshlrev_b32_e32 v122, 16, v206
	v_and_b32_e32 v123, 0xffff0000, v206
	v_lshlrev_b32_e32 v124, 16, v207
	v_and_b32_e32 v125, 0xffff0000, v207
	v_pk_add_f32 v[122:123], v[112:113], v[122:123]
	v_pk_add_f32 v[124:125], v[114:115], v[124:125]
	v_cndmask_b32_e64 v114, v117, v123, s[0:1]
	v_cndmask_b32_e64 v112, v119, v125, s[0:1]
	v_cndmask_b32_e64 v113, v118, v124, s[0:1]
	v_cndmask_b32_e64 v115, v116, v122, s[0:1]
	v_mov_b32_dpp v200, v114 quad_perm:[1,0,3,2] row_mask:0xf bank_mask:0xf bound_ctrl:1
	v_mov_b32_dpp v201, v113 quad_perm:[1,0,3,2] row_mask:0xf bank_mask:0xf bound_ctrl:1
	v_mov_b32_dpp v147, v115 quad_perm:[1,0,3,2] row_mask:0xf bank_mask:0xf bound_ctrl:1
	v_mov_b32_dpp v202, v112 quad_perm:[1,0,3,2] row_mask:0xf bank_mask:0xf bound_ctrl:1
	v_cndmask_b32_e64 v115, v202, v119, s[0:1]
	v_cndmask_b32_e64 v114, v201, v118, s[0:1]
	v_cndmask_b32_e64 v113, v200, v117, s[0:1]
	v_cndmask_b32_e64 v112, v147, v116, s[0:1]
	global_store_dwordx4 v[198:199], v[112:115], off offset:512 nt
	s_waitcnt vmcnt(30)
	v_lshlrev_b32_e32 v116, 16, v215
	v_and_b32_e32 v117, 0xffff0000, v215
	v_cndmask_b32_e64 v115, v125, v202, s[0:1]
	v_cndmask_b32_e64 v114, v124, v201, s[0:1]
	v_cndmask_b32_e64 v113, v123, v200, s[0:1]
	v_cndmask_b32_e64 v112, v122, v147, s[0:1]
	global_store_dwordx4 v[126:127], v[112:115], off offset:512 nt
	v_pk_add_f32 v[110:111], v[110:111], v[116:117]
	s_waitcnt vmcnt(30)
	v_lshlrev_b32_e32 v116, 16, v217
	v_lshlrev_b32_e32 v114, 16, v214
	v_and_b32_e32 v115, 0xffff0000, v214
	v_pk_add_f32 v[108:109], v[108:109], v[114:115]
	v_lshlrev_b32_e32 v114, 16, v216
	v_and_b32_e32 v115, 0xffff0000, v216
	v_and_b32_e32 v117, 0xffff0000, v217
	v_pk_add_f32 v[114:115], v[104:105], v[114:115]
	v_add_u32_e32 v112, 16, v146
	v_pk_add_f32 v[116:117], v[106:107], v[116:117]
	v_cndmask_b32_e64 v106, v109, v115, s[0:1]
	v_cndmask_b32_e64 v107, v108, v114, s[0:1]
	v_ashrrev_i32_e32 v113, 31, v112
	v_cndmask_b32_e64 v104, v111, v117, s[0:1]
	v_cndmask_b32_e64 v105, v110, v116, s[0:1]
	v_mov_b32_dpp v118, v107 quad_perm:[1,0,3,2] row_mask:0xf bank_mask:0xf bound_ctrl:1
	v_mov_b32_dpp v119, v106 quad_perm:[1,0,3,2] row_mask:0xf bank_mask:0xf bound_ctrl:1
	v_mov_b32_dpp v122, v105 quad_perm:[1,0,3,2] row_mask:0xf bank_mask:0xf bound_ctrl:1
	v_mov_b32_dpp v123, v104 quad_perm:[1,0,3,2] row_mask:0xf bank_mask:0xf bound_ctrl:1
	v_cndmask_b32_e64 v105, v119, v109, s[0:1]
	v_cndmask_b32_e64 v104, v118, v108, s[0:1]
	v_lshlrev_b64 v[108:109], 12, v[112:113]
	v_lshl_add_u64 v[108:109], s[74:75], 0, v[108:109]
	v_lshl_add_u64 v[108:109], v[108:109], 0, v[120:121]
	v_cndmask_b32_e64 v107, v123, v111, s[0:1]
	v_cndmask_b32_e64 v106, v122, v110, s[0:1]
	v_add_co_u32_e32 v110, vcc, s52, v108
	global_store_dwordx4 v[108:109], v[104:107], off nt
	s_nop 0
	v_addc_co_u32_e32 v111, vcc, 0, v109, vcc
	v_cndmask_b32_e64 v107, v117, v123, s[0:1]
	v_cndmask_b32_e64 v106, v116, v122, s[0:1]
	v_cndmask_b32_e64 v105, v115, v119, s[0:1]
	v_cndmask_b32_e64 v104, v114, v118, s[0:1]
	global_store_dwordx4 v[110:111], v[104:107], off nt
	s_nop 1
	s_waitcnt vmcnt(31)
	v_lshlrev_b32_e32 v104, 16, v218
	v_and_b32_e32 v105, 0xffff0000, v218
	v_lshlrev_b32_e32 v106, 16, v219
	v_and_b32_e32 v107, 0xffff0000, v219
	v_pk_add_f32 v[100:101], v[100:101], v[104:105]
	v_pk_add_f32 v[102:103], v[102:103], v[106:107]
	s_waitcnt vmcnt(30)
	v_lshlrev_b32_e32 v104, 16, v220
	v_and_b32_e32 v105, 0xffff0000, v220
	v_lshlrev_b32_e32 v106, 16, v221
	v_and_b32_e32 v107, 0xffff0000, v221
	v_pk_add_f32 v[104:105], v[96:97], v[104:105]
	v_pk_add_f32 v[106:107], v[98:99], v[106:107]
	v_cndmask_b32_e64 v98, v101, v105, s[0:1]
	v_cndmask_b32_e64 v96, v103, v107, s[0:1]
	v_cndmask_b32_e64 v97, v102, v106, s[0:1]
	v_cndmask_b32_e64 v99, v100, v104, s[0:1]
	v_mov_b32_dpp v113, v98 quad_perm:[1,0,3,2] row_mask:0xf bank_mask:0xf bound_ctrl:1
	v_mov_b32_dpp v114, v97 quad_perm:[1,0,3,2] row_mask:0xf bank_mask:0xf bound_ctrl:1
	v_mov_b32_dpp v112, v99 quad_perm:[1,0,3,2] row_mask:0xf bank_mask:0xf bound_ctrl:1
	v_mov_b32_dpp v115, v96 quad_perm:[1,0,3,2] row_mask:0xf bank_mask:0xf bound_ctrl:1
	v_cndmask_b32_e64 v99, v115, v103, s[0:1]
	v_cndmask_b32_e64 v98, v114, v102, s[0:1]
	v_cndmask_b32_e64 v97, v113, v101, s[0:1]
	v_cndmask_b32_e64 v96, v112, v100, s[0:1]
	global_store_dwordx4 v[108:109], v[96:99], off offset:512 nt
	s_waitcnt vmcnt(30)
	v_lshlrev_b32_e32 v100, 16, v191
	v_and_b32_e32 v101, 0xffff0000, v191
	v_cndmask_b32_e64 v99, v107, v115, s[0:1]
	v_cndmask_b32_e64 v98, v106, v114, s[0:1]
	v_cndmask_b32_e64 v97, v105, v113, s[0:1]
	v_cndmask_b32_e64 v96, v104, v112, s[0:1]
	global_store_dwordx4 v[110:111], v[96:99], off offset:512 nt
	v_pk_add_f32 v[94:95], v[94:95], v[100:101]
	s_waitcnt vmcnt(30)
	v_lshlrev_b32_e32 v100, 16, v189
	v_lshlrev_b32_e32 v98, 16, v190
	v_and_b32_e32 v99, 0xffff0000, v190
	v_pk_add_f32 v[92:93], v[92:93], v[98:99]
	v_lshlrev_b32_e32 v98, 16, v188
	v_and_b32_e32 v99, 0xffff0000, v188
	v_and_b32_e32 v101, 0xffff0000, v189
	v_pk_add_f32 v[98:99], v[88:89], v[98:99]
	v_add_u32_e32 v96, 32, v146
	v_pk_add_f32 v[100:101], v[90:91], v[100:101]
	v_cndmask_b32_e64 v90, v93, v99, s[0:1]
	v_cndmask_b32_e64 v91, v92, v98, s[0:1]
	v_ashrrev_i32_e32 v97, 31, v96
	v_cndmask_b32_e64 v88, v95, v101, s[0:1]
	v_cndmask_b32_e64 v89, v94, v100, s[0:1]
	v_mov_b32_dpp v102, v91 quad_perm:[1,0,3,2] row_mask:0xf bank_mask:0xf bound_ctrl:1
	v_mov_b32_dpp v103, v90 quad_perm:[1,0,3,2] row_mask:0xf bank_mask:0xf bound_ctrl:1
	v_mov_b32_dpp v104, v89 quad_perm:[1,0,3,2] row_mask:0xf bank_mask:0xf bound_ctrl:1
	v_mov_b32_dpp v105, v88 quad_perm:[1,0,3,2] row_mask:0xf bank_mask:0xf bound_ctrl:1
	v_cndmask_b32_e64 v89, v103, v93, s[0:1]
	v_cndmask_b32_e64 v88, v102, v92, s[0:1]
	v_lshlrev_b64 v[92:93], 12, v[96:97]
	v_lshl_add_u64 v[92:93], s[74:75], 0, v[92:93]
	v_lshl_add_u64 v[92:93], v[92:93], 0, v[120:121]
	v_cndmask_b32_e64 v91, v105, v95, s[0:1]
	v_cndmask_b32_e64 v90, v104, v94, s[0:1]
	v_add_co_u32_e32 v94, vcc, s52, v92
	global_store_dwordx4 v[92:93], v[88:91], off nt
	s_nop 0
	v_addc_co_u32_e32 v95, vcc, 0, v93, vcc
	v_cndmask_b32_e64 v91, v101, v105, s[0:1]
	v_cndmask_b32_e64 v90, v100, v104, s[0:1]
	v_cndmask_b32_e64 v89, v99, v103, s[0:1]
	v_cndmask_b32_e64 v88, v98, v102, s[0:1]
	global_store_dwordx4 v[94:95], v[88:91], off nt
	s_nop 1
	s_waitcnt vmcnt(31)
	v_lshlrev_b32_e32 v88, 16, v186
	v_and_b32_e32 v89, 0xffff0000, v186
	v_lshlrev_b32_e32 v90, 16, v187
	v_and_b32_e32 v91, 0xffff0000, v187
	v_pk_add_f32 v[84:85], v[84:85], v[88:89]
	v_pk_add_f32 v[86:87], v[86:87], v[90:91]
	s_waitcnt vmcnt(30)
	v_lshlrev_b32_e32 v88, 16, v184
	v_and_b32_e32 v89, 0xffff0000, v184
	v_lshlrev_b32_e32 v90, 16, v185
	v_and_b32_e32 v91, 0xffff0000, v185
	v_pk_add_f32 v[88:89], v[80:81], v[88:89]
	v_pk_add_f32 v[90:91], v[82:83], v[90:91]
	v_cndmask_b32_e64 v82, v85, v89, s[0:1]
	v_cndmask_b32_e64 v80, v87, v91, s[0:1]
	v_cndmask_b32_e64 v81, v86, v90, s[0:1]
	v_cndmask_b32_e64 v83, v84, v88, s[0:1]
	v_mov_b32_dpp v97, v82 quad_perm:[1,0,3,2] row_mask:0xf bank_mask:0xf bound_ctrl:1
	v_mov_b32_dpp v98, v81 quad_perm:[1,0,3,2] row_mask:0xf bank_mask:0xf bound_ctrl:1
	v_mov_b32_dpp v96, v83 quad_perm:[1,0,3,2] row_mask:0xf bank_mask:0xf bound_ctrl:1
	v_mov_b32_dpp v99, v80 quad_perm:[1,0,3,2] row_mask:0xf bank_mask:0xf bound_ctrl:1
	v_cndmask_b32_e64 v83, v99, v87, s[0:1]
	v_cndmask_b32_e64 v82, v98, v86, s[0:1]
	v_cndmask_b32_e64 v81, v97, v85, s[0:1]
	v_cndmask_b32_e64 v80, v96, v84, s[0:1]
	global_store_dwordx4 v[92:93], v[80:83], off offset:512 nt
	s_waitcnt vmcnt(30)
	v_lshlrev_b32_e32 v84, 16, v183
	v_and_b32_e32 v85, 0xffff0000, v183
	v_cndmask_b32_e64 v83, v91, v99, s[0:1]
	v_cndmask_b32_e64 v82, v90, v98, s[0:1]
	v_cndmask_b32_e64 v81, v89, v97, s[0:1]
	v_cndmask_b32_e64 v80, v88, v96, s[0:1]
	global_store_dwordx4 v[94:95], v[80:83], off offset:512 nt
	v_pk_add_f32 v[78:79], v[78:79], v[84:85]
	s_waitcnt vmcnt(30)
	v_lshlrev_b32_e32 v84, 16, v181
	v_lshlrev_b32_e32 v82, 16, v182
	v_and_b32_e32 v83, 0xffff0000, v182
	v_pk_add_f32 v[76:77], v[76:77], v[82:83]
	v_lshlrev_b32_e32 v82, 16, v180
	v_and_b32_e32 v83, 0xffff0000, v180
	v_and_b32_e32 v85, 0xffff0000, v181
	v_pk_add_f32 v[82:83], v[72:73], v[82:83]
	v_add_u32_e32 v80, 48, v146
	v_pk_add_f32 v[84:85], v[74:75], v[84:85]
	v_cndmask_b32_e64 v74, v77, v83, s[0:1]
	v_cndmask_b32_e64 v75, v76, v82, s[0:1]
	v_ashrrev_i32_e32 v81, 31, v80
	v_cndmask_b32_e64 v72, v79, v85, s[0:1]
	v_cndmask_b32_e64 v73, v78, v84, s[0:1]
	v_mov_b32_dpp v86, v75 quad_perm:[1,0,3,2] row_mask:0xf bank_mask:0xf bound_ctrl:1
	v_mov_b32_dpp v87, v74 quad_perm:[1,0,3,2] row_mask:0xf bank_mask:0xf bound_ctrl:1
	v_mov_b32_dpp v88, v73 quad_perm:[1,0,3,2] row_mask:0xf bank_mask:0xf bound_ctrl:1
	v_mov_b32_dpp v89, v72 quad_perm:[1,0,3,2] row_mask:0xf bank_mask:0xf bound_ctrl:1
	v_cndmask_b32_e64 v73, v87, v77, s[0:1]
	v_cndmask_b32_e64 v72, v86, v76, s[0:1]
	v_lshlrev_b64 v[76:77], 12, v[80:81]
	v_lshl_add_u64 v[76:77], s[74:75], 0, v[76:77]
	v_lshl_add_u64 v[76:77], v[76:77], 0, v[120:121]
	v_cndmask_b32_e64 v75, v89, v79, s[0:1]
	v_cndmask_b32_e64 v74, v88, v78, s[0:1]
	v_add_co_u32_e32 v78, vcc, s52, v76
	global_store_dwordx4 v[76:77], v[72:75], off nt
	s_nop 0
	v_addc_co_u32_e32 v79, vcc, 0, v77, vcc
	v_cndmask_b32_e64 v75, v85, v89, s[0:1]
	v_cndmask_b32_e64 v74, v84, v88, s[0:1]
	v_cndmask_b32_e64 v73, v83, v87, s[0:1]
	v_cndmask_b32_e64 v72, v82, v86, s[0:1]
	global_store_dwordx4 v[78:79], v[72:75], off nt
	s_nop 1
	s_waitcnt vmcnt(31)
	v_lshlrev_b32_e32 v72, 16, v178
	v_and_b32_e32 v73, 0xffff0000, v178
	v_lshlrev_b32_e32 v74, 16, v179
	v_and_b32_e32 v75, 0xffff0000, v179
	v_pk_add_f32 v[68:69], v[68:69], v[72:73]
	v_pk_add_f32 v[70:71], v[70:71], v[74:75]
	s_waitcnt vmcnt(30)
	v_lshlrev_b32_e32 v72, 16, v176
	v_and_b32_e32 v73, 0xffff0000, v176
	v_lshlrev_b32_e32 v74, 16, v177
	v_and_b32_e32 v75, 0xffff0000, v177
	v_pk_add_f32 v[72:73], v[64:65], v[72:73]
	v_pk_add_f32 v[74:75], v[66:67], v[74:75]
	v_cndmask_b32_e64 v66, v69, v73, s[0:1]
	v_cndmask_b32_e64 v64, v71, v75, s[0:1]
	v_cndmask_b32_e64 v65, v70, v74, s[0:1]
	v_cndmask_b32_e64 v67, v68, v72, s[0:1]
	v_mov_b32_dpp v81, v66 quad_perm:[1,0,3,2] row_mask:0xf bank_mask:0xf bound_ctrl:1
	v_mov_b32_dpp v82, v65 quad_perm:[1,0,3,2] row_mask:0xf bank_mask:0xf bound_ctrl:1
	v_mov_b32_dpp v80, v67 quad_perm:[1,0,3,2] row_mask:0xf bank_mask:0xf bound_ctrl:1
	v_mov_b32_dpp v83, v64 quad_perm:[1,0,3,2] row_mask:0xf bank_mask:0xf bound_ctrl:1
	v_cndmask_b32_e64 v67, v83, v71, s[0:1]
	v_cndmask_b32_e64 v66, v82, v70, s[0:1]
	v_cndmask_b32_e64 v65, v81, v69, s[0:1]
	v_cndmask_b32_e64 v64, v80, v68, s[0:1]
	global_store_dwordx4 v[76:77], v[64:67], off offset:512 nt
	s_waitcnt vmcnt(30)
	v_lshlrev_b32_e32 v68, 16, v175
	v_and_b32_e32 v69, 0xffff0000, v175
	v_cndmask_b32_e64 v67, v75, v83, s[0:1]
	v_cndmask_b32_e64 v66, v74, v82, s[0:1]
	v_cndmask_b32_e64 v65, v73, v81, s[0:1]
	v_cndmask_b32_e64 v64, v72, v80, s[0:1]
	global_store_dwordx4 v[78:79], v[64:67], off offset:512 nt
	v_pk_add_f32 v[62:63], v[62:63], v[68:69]
	s_waitcnt vmcnt(30)
	v_lshlrev_b32_e32 v68, 16, v173
	v_lshlrev_b32_e32 v66, 16, v174
	v_and_b32_e32 v67, 0xffff0000, v174
	v_pk_add_f32 v[60:61], v[60:61], v[66:67]
	v_lshlrev_b32_e32 v66, 16, v172
	v_and_b32_e32 v67, 0xffff0000, v172
	v_and_b32_e32 v69, 0xffff0000, v173
	v_pk_add_f32 v[66:67], v[56:57], v[66:67]
	v_add_u32_e32 v64, 0x80, v146
	v_pk_add_f32 v[68:69], v[58:59], v[68:69]
	v_cndmask_b32_e64 v58, v61, v67, s[0:1]
	v_cndmask_b32_e64 v59, v60, v66, s[0:1]
	v_ashrrev_i32_e32 v65, 31, v64
	v_cndmask_b32_e64 v56, v63, v69, s[0:1]
	v_cndmask_b32_e64 v57, v62, v68, s[0:1]
	v_mov_b32_dpp v70, v59 quad_perm:[1,0,3,2] row_mask:0xf bank_mask:0xf bound_ctrl:1
	v_mov_b32_dpp v71, v58 quad_perm:[1,0,3,2] row_mask:0xf bank_mask:0xf bound_ctrl:1
	v_mov_b32_dpp v72, v57 quad_perm:[1,0,3,2] row_mask:0xf bank_mask:0xf bound_ctrl:1
	v_mov_b32_dpp v73, v56 quad_perm:[1,0,3,2] row_mask:0xf bank_mask:0xf bound_ctrl:1
	v_cndmask_b32_e64 v57, v71, v61, s[0:1]
	v_cndmask_b32_e64 v56, v70, v60, s[0:1]
	v_lshlrev_b64 v[60:61], 12, v[64:65]
	v_lshl_add_u64 v[60:61], s[74:75], 0, v[60:61]
	v_lshl_add_u64 v[60:61], v[60:61], 0, v[120:121]
	v_cndmask_b32_e64 v59, v73, v63, s[0:1]
	v_cndmask_b32_e64 v58, v72, v62, s[0:1]
	v_add_co_u32_e32 v62, vcc, s52, v60
	global_store_dwordx4 v[60:61], v[56:59], off nt
	s_nop 0
	v_addc_co_u32_e32 v63, vcc, 0, v61, vcc
	v_cndmask_b32_e64 v59, v69, v73, s[0:1]
	v_cndmask_b32_e64 v58, v68, v72, s[0:1]
	v_cndmask_b32_e64 v57, v67, v71, s[0:1]
	v_cndmask_b32_e64 v56, v66, v70, s[0:1]
	global_store_dwordx4 v[62:63], v[56:59], off nt
	s_nop 1
	s_waitcnt vmcnt(31)
	v_lshlrev_b32_e32 v56, 16, v170
	v_and_b32_e32 v57, 0xffff0000, v170
	v_lshlrev_b32_e32 v58, 16, v171
	v_and_b32_e32 v59, 0xffff0000, v171
	v_pk_add_f32 v[52:53], v[52:53], v[56:57]
	v_pk_add_f32 v[54:55], v[54:55], v[58:59]
	s_waitcnt vmcnt(30)
	v_lshlrev_b32_e32 v56, 16, v168
	v_and_b32_e32 v57, 0xffff0000, v168
	v_lshlrev_b32_e32 v58, 16, v169
	v_and_b32_e32 v59, 0xffff0000, v169
	v_pk_add_f32 v[56:57], v[48:49], v[56:57]
	v_pk_add_f32 v[58:59], v[50:51], v[58:59]
	v_cndmask_b32_e64 v50, v53, v57, s[0:1]
	v_cndmask_b32_e64 v48, v55, v59, s[0:1]
	v_cndmask_b32_e64 v49, v54, v58, s[0:1]
	v_cndmask_b32_e64 v51, v52, v56, s[0:1]
	v_mov_b32_dpp v65, v50 quad_perm:[1,0,3,2] row_mask:0xf bank_mask:0xf bound_ctrl:1
	v_mov_b32_dpp v66, v49 quad_perm:[1,0,3,2] row_mask:0xf bank_mask:0xf bound_ctrl:1
	v_mov_b32_dpp v64, v51 quad_perm:[1,0,3,2] row_mask:0xf bank_mask:0xf bound_ctrl:1
	v_mov_b32_dpp v67, v48 quad_perm:[1,0,3,2] row_mask:0xf bank_mask:0xf bound_ctrl:1
	v_cndmask_b32_e64 v51, v67, v55, s[0:1]
	v_cndmask_b32_e64 v50, v66, v54, s[0:1]
	v_cndmask_b32_e64 v49, v65, v53, s[0:1]
	v_cndmask_b32_e64 v48, v64, v52, s[0:1]
	global_store_dwordx4 v[60:61], v[48:51], off offset:512 nt
	s_waitcnt vmcnt(30)
	v_lshlrev_b32_e32 v52, 16, v167
	v_and_b32_e32 v53, 0xffff0000, v167
	v_cndmask_b32_e64 v51, v59, v67, s[0:1]
	v_cndmask_b32_e64 v50, v58, v66, s[0:1]
	v_cndmask_b32_e64 v49, v57, v65, s[0:1]
	v_cndmask_b32_e64 v48, v56, v64, s[0:1]
	global_store_dwordx4 v[62:63], v[48:51], off offset:512 nt
	v_pk_add_f32 v[46:47], v[46:47], v[52:53]
	s_waitcnt vmcnt(30)
	v_lshlrev_b32_e32 v52, 16, v165
	v_lshlrev_b32_e32 v50, 16, v166
	v_and_b32_e32 v51, 0xffff0000, v166
	v_pk_add_f32 v[44:45], v[44:45], v[50:51]
	v_lshlrev_b32_e32 v50, 16, v164
	v_and_b32_e32 v51, 0xffff0000, v164
	v_and_b32_e32 v53, 0xffff0000, v165
	v_pk_add_f32 v[50:51], v[40:41], v[50:51]
	v_add_u32_e32 v48, 0x90, v146
	v_pk_add_f32 v[52:53], v[42:43], v[52:53]
	v_cndmask_b32_e64 v42, v45, v51, s[0:1]
	v_cndmask_b32_e64 v43, v44, v50, s[0:1]
	v_ashrrev_i32_e32 v49, 31, v48
	v_cndmask_b32_e64 v40, v47, v53, s[0:1]
	v_cndmask_b32_e64 v41, v46, v52, s[0:1]
	v_mov_b32_dpp v54, v43 quad_perm:[1,0,3,2] row_mask:0xf bank_mask:0xf bound_ctrl:1
	v_mov_b32_dpp v55, v42 quad_perm:[1,0,3,2] row_mask:0xf bank_mask:0xf bound_ctrl:1
	v_mov_b32_dpp v56, v41 quad_perm:[1,0,3,2] row_mask:0xf bank_mask:0xf bound_ctrl:1
	v_mov_b32_dpp v57, v40 quad_perm:[1,0,3,2] row_mask:0xf bank_mask:0xf bound_ctrl:1
	v_cndmask_b32_e64 v41, v55, v45, s[0:1]
	v_cndmask_b32_e64 v40, v54, v44, s[0:1]
	v_lshlrev_b64 v[44:45], 12, v[48:49]
	v_lshl_add_u64 v[44:45], s[74:75], 0, v[44:45]
	v_lshl_add_u64 v[44:45], v[44:45], 0, v[120:121]
	v_cndmask_b32_e64 v43, v57, v47, s[0:1]
	v_cndmask_b32_e64 v42, v56, v46, s[0:1]
	v_add_co_u32_e32 v46, vcc, s52, v44
	global_store_dwordx4 v[44:45], v[40:43], off nt
	s_nop 0
	v_addc_co_u32_e32 v47, vcc, 0, v45, vcc
	v_cndmask_b32_e64 v43, v53, v57, s[0:1]
	v_cndmask_b32_e64 v42, v52, v56, s[0:1]
	v_cndmask_b32_e64 v41, v51, v55, s[0:1]
	v_cndmask_b32_e64 v40, v50, v54, s[0:1]
	global_store_dwordx4 v[46:47], v[40:43], off nt
	s_nop 1
	s_waitcnt vmcnt(31)
	v_lshlrev_b32_e32 v40, 16, v162
	v_and_b32_e32 v41, 0xffff0000, v162
	v_lshlrev_b32_e32 v42, 16, v163
	v_and_b32_e32 v43, 0xffff0000, v163
	v_pk_add_f32 v[36:37], v[36:37], v[40:41]
	v_pk_add_f32 v[38:39], v[38:39], v[42:43]
	s_waitcnt vmcnt(30)
	v_lshlrev_b32_e32 v40, 16, v160
	v_and_b32_e32 v41, 0xffff0000, v160
	v_lshlrev_b32_e32 v42, 16, v161
	v_and_b32_e32 v43, 0xffff0000, v161
	v_pk_add_f32 v[40:41], v[32:33], v[40:41]
	v_pk_add_f32 v[42:43], v[34:35], v[42:43]
	v_cndmask_b32_e64 v34, v37, v41, s[0:1]
	v_cndmask_b32_e64 v32, v39, v43, s[0:1]
	v_cndmask_b32_e64 v33, v38, v42, s[0:1]
	v_cndmask_b32_e64 v35, v36, v40, s[0:1]
	v_mov_b32_dpp v49, v34 quad_perm:[1,0,3,2] row_mask:0xf bank_mask:0xf bound_ctrl:1
	v_mov_b32_dpp v50, v33 quad_perm:[1,0,3,2] row_mask:0xf bank_mask:0xf bound_ctrl:1
	v_mov_b32_dpp v48, v35 quad_perm:[1,0,3,2] row_mask:0xf bank_mask:0xf bound_ctrl:1
	v_mov_b32_dpp v51, v32 quad_perm:[1,0,3,2] row_mask:0xf bank_mask:0xf bound_ctrl:1
	v_cndmask_b32_e64 v35, v51, v39, s[0:1]
	v_cndmask_b32_e64 v34, v50, v38, s[0:1]
	v_cndmask_b32_e64 v33, v49, v37, s[0:1]
	v_cndmask_b32_e64 v32, v48, v36, s[0:1]
	global_store_dwordx4 v[44:45], v[32:35], off offset:512 nt
	s_waitcnt vmcnt(30)
	v_lshlrev_b32_e32 v36, 16, v159
	v_and_b32_e32 v37, 0xffff0000, v159
	v_cndmask_b32_e64 v35, v43, v51, s[0:1]
	v_cndmask_b32_e64 v34, v42, v50, s[0:1]
	v_cndmask_b32_e64 v33, v41, v49, s[0:1]
	v_cndmask_b32_e64 v32, v40, v48, s[0:1]
	global_store_dwordx4 v[46:47], v[32:35], off offset:512 nt
	v_pk_add_f32 v[30:31], v[30:31], v[36:37]
	s_waitcnt vmcnt(30)
	v_lshlrev_b32_e32 v36, 16, v157
	v_lshlrev_b32_e32 v34, 16, v158
	v_and_b32_e32 v35, 0xffff0000, v158
	v_pk_add_f32 v[28:29], v[28:29], v[34:35]
	v_lshlrev_b32_e32 v34, 16, v156
	v_and_b32_e32 v35, 0xffff0000, v156
	v_and_b32_e32 v37, 0xffff0000, v157
	v_pk_add_f32 v[34:35], v[24:25], v[34:35]
	v_add_u32_e32 v32, 0xa0, v146
	v_pk_add_f32 v[36:37], v[26:27], v[36:37]
	v_cndmask_b32_e64 v26, v29, v35, s[0:1]
	v_cndmask_b32_e64 v27, v28, v34, s[0:1]
	v_ashrrev_i32_e32 v33, 31, v32
	v_cndmask_b32_e64 v24, v31, v37, s[0:1]
	v_cndmask_b32_e64 v25, v30, v36, s[0:1]
	v_mov_b32_dpp v38, v27 quad_perm:[1,0,3,2] row_mask:0xf bank_mask:0xf bound_ctrl:1
	v_mov_b32_dpp v39, v26 quad_perm:[1,0,3,2] row_mask:0xf bank_mask:0xf bound_ctrl:1
	v_mov_b32_dpp v40, v25 quad_perm:[1,0,3,2] row_mask:0xf bank_mask:0xf bound_ctrl:1
	v_mov_b32_dpp v41, v24 quad_perm:[1,0,3,2] row_mask:0xf bank_mask:0xf bound_ctrl:1
	v_cndmask_b32_e64 v25, v39, v29, s[0:1]
	v_cndmask_b32_e64 v24, v38, v28, s[0:1]
	v_lshlrev_b64 v[28:29], 12, v[32:33]
	v_lshl_add_u64 v[28:29], s[74:75], 0, v[28:29]
	v_lshl_add_u64 v[28:29], v[28:29], 0, v[120:121]
	v_cndmask_b32_e64 v27, v41, v31, s[0:1]
	v_cndmask_b32_e64 v26, v40, v30, s[0:1]
	v_add_co_u32_e32 v30, vcc, s52, v28
	global_store_dwordx4 v[28:29], v[24:27], off nt
	s_nop 0
	v_addc_co_u32_e32 v31, vcc, 0, v29, vcc
	v_cndmask_b32_e64 v27, v37, v41, s[0:1]
	v_cndmask_b32_e64 v26, v36, v40, s[0:1]
	v_cndmask_b32_e64 v25, v35, v39, s[0:1]
	v_cndmask_b32_e64 v24, v34, v38, s[0:1]
	global_store_dwordx4 v[30:31], v[24:27], off nt
	s_nop 1
	s_waitcnt vmcnt(31)
	v_lshlrev_b32_e32 v24, 16, v154
	v_and_b32_e32 v25, 0xffff0000, v154
	v_lshlrev_b32_e32 v26, 16, v155
	v_and_b32_e32 v27, 0xffff0000, v155
	v_pk_add_f32 v[20:21], v[20:21], v[24:25]
	v_pk_add_f32 v[22:23], v[22:23], v[26:27]
	s_waitcnt vmcnt(30)
	v_lshlrev_b32_e32 v24, 16, v152
	v_and_b32_e32 v25, 0xffff0000, v152
	v_lshlrev_b32_e32 v26, 16, v153
	v_and_b32_e32 v27, 0xffff0000, v153
	v_pk_add_f32 v[24:25], v[16:17], v[24:25]
	v_pk_add_f32 v[26:27], v[18:19], v[26:27]
	v_cndmask_b32_e64 v18, v21, v25, s[0:1]
	v_cndmask_b32_e64 v16, v23, v27, s[0:1]
	v_cndmask_b32_e64 v17, v22, v26, s[0:1]
	v_cndmask_b32_e64 v19, v20, v24, s[0:1]
	v_mov_b32_dpp v33, v18 quad_perm:[1,0,3,2] row_mask:0xf bank_mask:0xf bound_ctrl:1
	v_mov_b32_dpp v34, v17 quad_perm:[1,0,3,2] row_mask:0xf bank_mask:0xf bound_ctrl:1
	v_mov_b32_dpp v32, v19 quad_perm:[1,0,3,2] row_mask:0xf bank_mask:0xf bound_ctrl:1
	v_mov_b32_dpp v35, v16 quad_perm:[1,0,3,2] row_mask:0xf bank_mask:0xf bound_ctrl:1
	v_cndmask_b32_e64 v19, v35, v23, s[0:1]
	v_cndmask_b32_e64 v18, v34, v22, s[0:1]
	v_cndmask_b32_e64 v17, v33, v21, s[0:1]
	v_cndmask_b32_e64 v16, v32, v20, s[0:1]
	global_store_dwordx4 v[28:29], v[16:19], off offset:512 nt
	s_waitcnt vmcnt(30)
	v_lshlrev_b32_e32 v20, 16, v151
	v_and_b32_e32 v21, 0xffff0000, v151
	v_cndmask_b32_e64 v19, v27, v35, s[0:1]
	v_cndmask_b32_e64 v18, v26, v34, s[0:1]
	v_cndmask_b32_e64 v17, v25, v33, s[0:1]
	v_cndmask_b32_e64 v16, v24, v32, s[0:1]
	global_store_dwordx4 v[30:31], v[16:19], off offset:512 nt
	v_pk_add_f32 v[14:15], v[14:15], v[20:21]
	s_waitcnt vmcnt(30)
	v_lshlrev_b32_e32 v20, 16, v149
	v_lshlrev_b32_e32 v18, 16, v150
	v_and_b32_e32 v19, 0xffff0000, v150
	v_pk_add_f32 v[12:13], v[12:13], v[18:19]
	v_lshlrev_b32_e32 v18, 16, v148
	v_and_b32_e32 v19, 0xffff0000, v148
	v_and_b32_e32 v21, 0xffff0000, v149
	v_pk_add_f32 v[18:19], v[8:9], v[18:19]
	v_add_u32_e32 v16, 0xb0, v146
	v_pk_add_f32 v[20:21], v[10:11], v[20:21]
	v_cndmask_b32_e64 v10, v13, v19, s[0:1]
	v_cndmask_b32_e64 v11, v12, v18, s[0:1]
	v_ashrrev_i32_e32 v17, 31, v16
	v_cndmask_b32_e64 v8, v15, v21, s[0:1]
	v_cndmask_b32_e64 v9, v14, v20, s[0:1]
	v_mov_b32_dpp v22, v11 quad_perm:[1,0,3,2] row_mask:0xf bank_mask:0xf bound_ctrl:1
	v_mov_b32_dpp v23, v10 quad_perm:[1,0,3,2] row_mask:0xf bank_mask:0xf bound_ctrl:1
	v_mov_b32_dpp v24, v9 quad_perm:[1,0,3,2] row_mask:0xf bank_mask:0xf bound_ctrl:1
	v_mov_b32_dpp v25, v8 quad_perm:[1,0,3,2] row_mask:0xf bank_mask:0xf bound_ctrl:1
	v_cndmask_b32_e64 v9, v23, v13, s[0:1]
	v_cndmask_b32_e64 v8, v22, v12, s[0:1]
	v_lshlrev_b64 v[12:13], 12, v[16:17]
	v_lshl_add_u64 v[12:13], s[74:75], 0, v[12:13]
	v_lshl_add_u64 v[12:13], v[12:13], 0, v[120:121]
	v_cndmask_b32_e64 v11, v25, v15, s[0:1]
	v_cndmask_b32_e64 v10, v24, v14, s[0:1]
	v_add_co_u32_e32 v14, vcc, s52, v12
	global_store_dwordx4 v[12:13], v[8:11], off nt
	s_nop 0
	v_addc_co_u32_e32 v15, vcc, 0, v13, vcc
	v_cndmask_b32_e64 v11, v21, v25, s[0:1]
	v_cndmask_b32_e64 v10, v20, v24, s[0:1]
	v_cndmask_b32_e64 v9, v19, v23, s[0:1]
	v_cndmask_b32_e64 v8, v18, v22, s[0:1]
	global_store_dwordx4 v[14:15], v[8:11], off nt
	s_andn2_b64 vcc, exec, s[4:5]
	s_mov_b64 s[4:5], -1
	s_waitcnt vmcnt(31)
	v_lshlrev_b32_e32 v8, 16, v144
	v_and_b32_e32 v9, 0xffff0000, v144
	v_lshlrev_b32_e32 v10, 16, v145
	v_and_b32_e32 v11, 0xffff0000, v145
	v_pk_add_f32 v[4:5], v[4:5], v[8:9]
	v_pk_add_f32 v[6:7], v[6:7], v[10:11]
	s_waitcnt vmcnt(30)
	v_lshlrev_b32_e32 v8, 16, v142
	v_and_b32_e32 v9, 0xffff0000, v142
	v_lshlrev_b32_e32 v10, 16, v143
	v_and_b32_e32 v11, 0xffff0000, v143
	v_pk_add_f32 v[8:9], v[0:1], v[8:9]
	v_pk_add_f32 v[10:11], v[2:3], v[10:11]
	v_cndmask_b32_e64 v2, v5, v9, s[0:1]
	v_cndmask_b32_e64 v0, v7, v11, s[0:1]
	v_cndmask_b32_e64 v1, v6, v10, s[0:1]
	v_cndmask_b32_e64 v3, v4, v8, s[0:1]
	v_mov_b32_dpp v17, v2 quad_perm:[1,0,3,2] row_mask:0xf bank_mask:0xf bound_ctrl:1
	v_mov_b32_dpp v18, v1 quad_perm:[1,0,3,2] row_mask:0xf bank_mask:0xf bound_ctrl:1
	v_mov_b32_dpp v16, v3 quad_perm:[1,0,3,2] row_mask:0xf bank_mask:0xf bound_ctrl:1
	v_mov_b32_dpp v19, v0 quad_perm:[1,0,3,2] row_mask:0xf bank_mask:0xf bound_ctrl:1
	v_cndmask_b32_e64 v3, v19, v7, s[0:1]
	v_cndmask_b32_e64 v2, v18, v6, s[0:1]
	v_cndmask_b32_e64 v1, v17, v5, s[0:1]
	v_cndmask_b32_e64 v0, v16, v4, s[0:1]
	global_store_dwordx4 v[12:13], v[0:3], off offset:512 nt
	s_nop 1
	v_cndmask_b32_e64 v3, v11, v19, s[0:1]
	v_cndmask_b32_e64 v2, v10, v18, s[0:1]
	v_cndmask_b32_e64 v1, v9, v17, s[0:1]
	v_cndmask_b32_e64 v0, v8, v16, s[0:1]
	global_store_dwordx4 v[14:15], v[0:3], off offset:512 nt
	s_cbranch_vccnz .LBB0_820
	s_andn2_b64 vcc, exec, s[6:7]
	s_cbranch_vccnz .LBB0_819
	s_mov_b32 s98, 1
	s_branch .LBB0_819
